# A/B input-projection GEMM epilogue (kind 0) rewritten as a straight block for single-destination column tiles
# speedup vs baseline: 1.0038x; 1.0038x over previous
; template <class F>
; DI void gemm_phase(const int tid, LAS unsigned char* lds, const bf16_t* Ap, int lda, const bf16_t* Bp, int ldb, int M, int N, int K, int G, int c, bool direct, const F& E) {
;     ...
;         else {
;             const int row0 = cur.pm * BM + wr * 64 + fr, col0 = cur.pn * BM + wc * 32 + 8 * fq;
; #pragma unroll
;             for (int ai = 0; ai < 2; ++ai)
; #pragma unroll
;                 for (int m = 0; m < 4; ++m)
; #pragma unroll
;                     for (int bj = 0; bj < 2; ++bj) E.st(row0 + ai * HALF + m * 16, col0 + bj * HALF, acc[ai][bj][m][0], acc[ai][bj][m][1]);
;         }
; DI void st8bf(bf16_t* dst, f32x4 v0, f32x4 v1) { u32x4 w; w.x = pk2(v0[0], v0[1]); w.y = pk2(v0[2], v0[3]); w.z = pk2(v1[0], v1[1]); w.w = pk2(v1[2], v1[3]); *(u32x4*)dst = w; }
;     DI void st(int row, int col, f32x4 v0, f32x4 v1) const {
;         switch (kind) {
;         case EK_ABIN: {
;             if (col < 256) st8bf(d0 + (size_t)row * 256 + col, v0, v1);
;             else if (col < 2560) st8bf(d1 + (size_t)row * 2304 + (col - 256), v0, v1);
;             else if (col < 3328) st8bf(d2 + (size_t)row * 768 + (col - 2560), v0, v1);
.Labin_epi:
	s_cmp_eq_u32 s70, 13
	s_cbranch_scc1 .Labin_back
	s_cmp_lt_u32 s70, 1
	s_cbranch_scc1 .Labin_c0
	s_cmp_lt_u32 s70, 10
	s_cbranch_scc1 .Labin_c1
	v_readlane_b32 s76, v254, 47
	v_readlane_b32 s77, v254, 48
	s_movk_i32 s80, 0x600
	s_sub_i32 s71, s70, 10
	s_branch .Labin_go
.Labin_c0:
	s_mov_b64 s[76:77], s[12:13]
	s_movk_i32 s80, 0x200
	s_mov_b32 s71, 0
	s_branch .Labin_go
.Labin_c1:
	s_mov_b64 s[76:77], s[14:15]
	s_movk_i32 s80, 0x1200
	s_sub_i32 s71, s70, 1
.Labin_go:
	s_lshl_b32 s71, s71, 8
	v_lshl_add_u32 v228, s36, 8, v183
	v_or_b32_e32 v229, s71, v194
	v_lshlrev_b32_e32 v229, 1, v229
	v_mad_u32_u24 v228, v228, s80, v229
	s_lshl_b32 s81, s80, 4
	s_mul_i32 s80, s81, 5
	v_cvt_pk_bf16_f32 v128, v124, v125
	v_cvt_pk_bf16_f32 v129, v126, v127
	v_cvt_pk_bf16_f32 v130, v120, v121
	v_cvt_pk_bf16_f32 v131, v122, v123
	global_store_dwordx4 v228, v[128:131], s[76:77]
	v_cvt_pk_bf16_f32 v132, v112, v113
	v_cvt_pk_bf16_f32 v133, v114, v115
	v_cvt_pk_bf16_f32 v134, v108, v109
	v_cvt_pk_bf16_f32 v135, v110, v111
	global_store_dwordx4 v228, v[132:135], s[76:77] offset:256
	s_add_u32 s76, s76, s81
	s_addc_u32 s77, s77, 0
	v_cvt_pk_bf16_f32 v136, v116, v117
	v_cvt_pk_bf16_f32 v137, v118, v119
	v_cvt_pk_bf16_f32 v138, v104, v105
	v_cvt_pk_bf16_f32 v139, v106, v107
	global_store_dwordx4 v228, v[136:139], s[76:77]
	v_cvt_pk_bf16_f32 v140, v96, v97
	v_cvt_pk_bf16_f32 v141, v98, v99
	v_cvt_pk_bf16_f32 v142, v92, v93
	v_cvt_pk_bf16_f32 v143, v94, v95
	global_store_dwordx4 v228, v[140:143], s[76:77] offset:256
	s_add_u32 s76, s76, s81
	s_addc_u32 s77, s77, 0
	v_cvt_pk_bf16_f32 v128, v100, v101
	v_cvt_pk_bf16_f32 v129, v102, v103
	v_cvt_pk_bf16_f32 v130, v88, v89
	v_cvt_pk_bf16_f32 v131, v90, v91
	global_store_dwordx4 v228, v[128:131], s[76:77]
	v_cvt_pk_bf16_f32 v132, v80, v81
	v_cvt_pk_bf16_f32 v133, v82, v83
	v_cvt_pk_bf16_f32 v134, v76, v77
	v_cvt_pk_bf16_f32 v135, v78, v79
	global_store_dwordx4 v228, v[132:135], s[76:77] offset:256
	s_add_u32 s76, s76, s81
	s_addc_u32 s77, s77, 0
	v_cvt_pk_bf16_f32 v136, v84, v85
	v_cvt_pk_bf16_f32 v137, v86, v87
	v_cvt_pk_bf16_f32 v138, v72, v73
	v_cvt_pk_bf16_f32 v139, v74, v75
	global_store_dwordx4 v228, v[136:139], s[76:77]
	v_cvt_pk_bf16_f32 v140, v68, v69
	v_cvt_pk_bf16_f32 v141, v70, v71
	v_cvt_pk_bf16_f32 v142, v64, v65
	v_cvt_pk_bf16_f32 v143, v66, v67
	global_store_dwordx4 v228, v[140:143], s[76:77] offset:256
	s_add_u32 s76, s76, s80
	s_addc_u32 s77, s77, 0
	v_cvt_pk_bf16_f32 v128, v60, v61
	v_cvt_pk_bf16_f32 v129, v62, v63
	v_cvt_pk_bf16_f32 v130, v56, v57
	v_cvt_pk_bf16_f32 v131, v58, v59
	global_store_dwordx4 v228, v[128:131], s[76:77]
	v_cvt_pk_bf16_f32 v132, v48, v49
	v_cvt_pk_bf16_f32 v133, v50, v51
	v_cvt_pk_bf16_f32 v134, v44, v45
	v_cvt_pk_bf16_f32 v135, v46, v47
	global_store_dwordx4 v228, v[132:135], s[76:77] offset:256
	s_add_u32 s76, s76, s81
	s_addc_u32 s77, s77, 0
	v_cvt_pk_bf16_f32 v136, v52, v53
	v_cvt_pk_bf16_f32 v137, v54, v55
	v_cvt_pk_bf16_f32 v138, v40, v41
	v_cvt_pk_bf16_f32 v139, v42, v43
	global_store_dwordx4 v228, v[136:139], s[76:77]
	v_cvt_pk_bf16_f32 v140, v24, v25
	v_cvt_pk_bf16_f32 v141, v26, v27
	v_cvt_pk_bf16_f32 v142, v20, v21
	v_cvt_pk_bf16_f32 v143, v22, v23
	global_store_dwordx4 v228, v[140:143], s[76:77] offset:256
	s_add_u32 s76, s76, s81
	s_addc_u32 s77, s77, 0
	v_cvt_pk_bf16_f32 v128, v36, v37
	v_cvt_pk_bf16_f32 v129, v38, v39
	v_cvt_pk_bf16_f32 v130, v16, v17
	v_cvt_pk_bf16_f32 v131, v18, v19
	global_store_dwordx4 v228, v[128:131], s[76:77]
	v_cvt_pk_bf16_f32 v132, v28, v29
	v_cvt_pk_bf16_f32 v133, v30, v31
	v_cvt_pk_bf16_f32 v134, v32, v33
	v_cvt_pk_bf16_f32 v135, v34, v35
	global_store_dwordx4 v228, v[132:135], s[76:77] offset:256
	s_add_u32 s76, s76, s81
	s_addc_u32 s77, s77, 0
	v_cvt_pk_bf16_f32 v136, v12, v13
	v_cvt_pk_bf16_f32 v137, v14, v15
	v_cvt_pk_bf16_f32 v138, v0, v1
	v_cvt_pk_bf16_f32 v139, v2, v3
	global_store_dwordx4 v228, v[136:139], s[76:77]
	v_cvt_pk_bf16_f32 v140, v8, v9
	v_cvt_pk_bf16_f32 v141, v10, v11
	v_cvt_pk_bf16_f32 v142, v4, v5
	v_cvt_pk_bf16_f32 v143, v6, v7
	global_store_dwordx4 v228, v[140:143], s[76:77] offset:256

; #define PG8_STAGE(bufoff, gbase, voff) do { _Pragma("unroll") for (int _i = 0; _i < 2; ++_i) \
;         __builtin_amdgcn_global_load_lds((const unsigned*)((const char*)(gbase) + (voff)[_i]), (LAS unsigned*)(lds + (bufoff) + ldsw + _i * 8192), 16, 0, 0); } while (0)
; #define PG8_LDA(dst, b, h) do { _Pragma("unroll") for (int m = 0; m < 4; ++m) _Pragma("unroll") for (int k = 0; k < 2; ++k) dst[m][k] = *(const LAS bf16x8*)(lds + PG8_SA(b, h) + aoff + m * 2048 + k * 1024); } while (0)
; #define PG8_LDB(dst, b, h) do { _Pragma("unroll") for (int n = 0; n < 2; ++n) _Pragma("unroll") for (int k = 0; k < 2; ++k) dst[n][k] = *(const LAS bf16x8*)(lds + PG8_SB(b, h) + boff + n * 2048 + k * 1024); } while (0)
; #define PG8_WAIT_V(n) asm volatile("s_waitcnt vmcnt(" #n ")" ::: "memory")
; #define PG8_WAIT_L(n) asm volatile("s_waitcnt lgkmcnt(" #n ")" ::: "memory")
; #define PG8_BAR __builtin_amdgcn_s_barrier()
; #define PG8_SCHED __builtin_amdgcn_sched_barrier(0)
; template <class F>
; DI void gemm_phase(const int tid, LAS unsigned char* lds, const bf16_t* Ap, int lda, const bf16_t* Bp, int ldb, int M, int N, int K, int G, int c, bool direct, const F& E) {
;     ...
;         for (int t = 0; t < nt; t += 2) {
;             const bool last = (t == nt - 2);
;             const char* a1 = cA + (size_t)(t + 1) * kstep;
;             const char* a2 = last ? nA : cA + (size_t)(t + 2) * kstep; const char* b2 = last ? nB : cB + (size_t)(t + 2) * kstep;
;             const char* a3 = a2 + kstep; const char* b3 = b2 + kstep;
;             PG8_LDB(B0, 0, 0); PG8_SCHED; PG8_LDA(At, 0, 0); PG8_STAGE(PG8_SA(1, 1), a1 + hsA, voffA);
;             PG8_WAIT_L(8); PG8_BAR; PG8_WAIT_L(0); PG8_MMA(0, 0, At, B0); PG8_BAR; PG8_SCHED;
;             PG8_LDB(B1, 0, 1); PG8_STAGE(PG8_SB(0, 0), b2, voffB);
;             PG8_BAR; PG8_WAIT_L(0); PG8_MMA(0, 1, At, B1); PG8_BAR;
;             PG8_LDA(At, 0, 1); PG8_STAGE(PG8_SA(0, 0), a2, voffA);
;             PG8_BAR; PG8_WAIT_L(0); PG8_MMA(1, 0, At, B0); PG8_BAR; PG8_SCHED;
;             PG8_STAGE(PG8_SB(0, 1), b2 + hsB, voffB);
;             PG8_WAIT_V(6); PG8_BAR; PG8_MMA(1, 1, At, B1); PG8_BAR;
;             PG8_LDB(B0, 1, 0); PG8_SCHED; PG8_LDA(At, 1, 0); PG8_STAGE(PG8_SA(0, 1), a2 + hsA, voffA);
;             PG8_WAIT_L(8); PG8_BAR; PG8_WAIT_L(0); PG8_MMA(0, 0, At, B0); PG8_BAR; PG8_SCHED;
.LBB0_657:
	s_add_i32 s81, s76, 2
	s_add_u32 s78, s74, 0x80
	s_addc_u32 s77, s75, 0
	s_add_i32 s82, 0, 0x10000
	v_add_u32_e32 v140, s82, v189
	ds_read_b128 v[128:131], v140
	ds_read_b128 v[132:135], v140 offset:1024
	ds_read_b128 v[136:139], v140 offset:2048
	ds_read_b128 v[140:143], v140 offset:3072
	s_cmp_eq_u32 s67, s76
	s_cselect_b32 s76, s0, s78
	s_cselect_b32 s77, s1, s77
	s_cselect_b32 s79, s5, s80
	s_cselect_b32 s78, s4, s71
	s_add_u32 s98, s78, 0x80
	s_addc_u32 s99, s79, 0
	s_add_u32 s100, s76, 0x80
	s_addc_u32 s101, s77, 0
	s_add_i32 m0, s28, 0xc000
	ds_read_b128 v[144:147], v197
	ds_read_b128 v[148:151], v197 offset:1024
	ds_read_b128 v[152:155], v197 offset:2048
	ds_read_b128 v[156:159], v197 offset:3072
	ds_read_b128 v[160:163], v197 offset:4096
	ds_read_b128 v[164:167], v197 offset:5120
	ds_read_b128 v[168:171], v197 offset:6144
	ds_read_b128 v[172:175], v197 offset:7168
	global_load_lds_dwordx4 v204, s[74:75]
	s_add_i32 m0, s28, 0xe000
	s_nop 0
	global_load_lds_dwordx4 v206, s[74:75]
	s_waitcnt lgkmcnt(8)
	s_barrier
	s_waitcnt lgkmcnt(0)
	s_waitcnt lgkmcnt(0)
	v_mfma_f32_16x16x32_bf16 v[124:127], v[128:131], v[144:147], v[124:127]
	v_mfma_f32_16x16x32_bf16 v[120:123], v[136:139], v[144:147], v[120:123]
	v_mfma_f32_16x16x32_bf16 v[116:119], v[128:131], v[152:155], v[116:119]
	v_mfma_f32_16x16x32_bf16 v[104:107], v[136:139], v[152:155], v[104:107]
	v_mfma_f32_16x16x32_bf16 v[100:103], v[128:131], v[160:163], v[100:103]
	v_mfma_f32_16x16x32_bf16 v[88:91], v[136:139], v[160:163], v[88:91]
	v_mfma_f32_16x16x32_bf16 v[84:87], v[128:131], v[168:171], v[84:87]
	v_mfma_f32_16x16x32_bf16 v[72:75], v[136:139], v[168:171], v[72:75]
	v_mfma_f32_16x16x32_bf16 v[124:127], v[132:135], v[148:151], v[124:127]
	v_mfma_f32_16x16x32_bf16 v[120:123], v[140:143], v[148:151], v[120:123]
	v_mfma_f32_16x16x32_bf16 v[116:119], v[132:135], v[156:159], v[116:119]
	v_mfma_f32_16x16x32_bf16 v[104:107], v[140:143], v[156:159], v[104:107]
	v_mfma_f32_16x16x32_bf16 v[100:103], v[132:135], v[164:167], v[100:103]
	v_mfma_f32_16x16x32_bf16 v[88:91], v[140:143], v[164:167], v[88:91]
	v_mfma_f32_16x16x32_bf16 v[84:87], v[132:135], v[172:175], v[84:87]
	v_mfma_f32_16x16x32_bf16 v[72:75], v[140:143], v[172:175], v[72:75]
	s_barrier
	s_add_i32 s82, s82, s27
	v_add_u32_e32 v180, s95, v189
	s_mov_b32 m0, s82
	ds_read_b128 v[208:211], v180
	ds_read_b128 v[212:215], v180 offset:1024
	ds_read_b128 v[216:219], v180 offset:2048
	ds_read_b128 v[220:223], v180 offset:3072
	global_load_lds_dwordx4 v178, s[78:79]
	s_add_i32 m0, s82, 0x2000
	s_nop 0
	global_load_lds_dwordx4 v186, s[78:79]
	s_barrier
	s_waitcnt lgkmcnt(0)
	s_waitcnt lgkmcnt(0)
	v_mfma_f32_16x16x32_bf16 v[112:115], v[208:211], v[144:147], v[112:115]
	v_mfma_f32_16x16x32_bf16 v[108:111], v[216:219], v[144:147], v[108:111]
	v_mfma_f32_16x16x32_bf16 v[96:99], v[208:211], v[152:155], v[96:99]
	v_mfma_f32_16x16x32_bf16 v[92:95], v[216:219], v[152:155], v[92:95]
	v_mfma_f32_16x16x32_bf16 v[80:83], v[208:211], v[160:163], v[80:83]
	v_mfma_f32_16x16x32_bf16 v[76:79], v[216:219], v[160:163], v[76:79]
	v_mfma_f32_16x16x32_bf16 v[68:71], v[208:211], v[168:171], v[68:71]
	v_mfma_f32_16x16x32_bf16 v[64:67], v[216:219], v[168:171], v[64:67]
	v_mfma_f32_16x16x32_bf16 v[112:115], v[212:215], v[148:151], v[112:115]
	v_mfma_f32_16x16x32_bf16 v[108:111], v[220:223], v[148:151], v[108:111]
	v_mfma_f32_16x16x32_bf16 v[96:99], v[212:215], v[156:159], v[96:99]
	v_mfma_f32_16x16x32_bf16 v[92:95], v[220:223], v[156:159], v[92:95]
	v_mfma_f32_16x16x32_bf16 v[80:83], v[212:215], v[164:167], v[80:83]
	v_mfma_f32_16x16x32_bf16 v[76:79], v[220:223], v[164:167], v[76:79]
	v_mfma_f32_16x16x32_bf16 v[68:71], v[212:215], v[172:175], v[68:71]
	v_mfma_f32_16x16x32_bf16 v[64:67], v[220:223], v[172:175], v[64:67]
	s_mov_b32 m0, s28
	s_barrier
	ds_read_b128 v[144:147], v197 offset:16384
	ds_read_b128 v[148:151], v197 offset:17408
	ds_read_b128 v[152:155], v197 offset:18432
	ds_read_b128 v[156:159], v197 offset:19456
	ds_read_b128 v[160:163], v197 offset:20480
	ds_read_b128 v[164:167], v197 offset:21504
	ds_read_b128 v[168:171], v197 offset:22528
	ds_read_b128 v[172:175], v197 offset:23552
	global_load_lds_dwordx4 v176, s[76:77]
	s_mov_b32 m0, s34
	s_nop 0
	global_load_lds_dwordx4 v184, s[76:77]
	s_barrier
	s_waitcnt lgkmcnt(0)
	s_waitcnt lgkmcnt(0)
	v_mfma_f32_16x16x32_bf16 v[60:63], v[128:131], v[144:147], v[60:63]
	v_mfma_f32_16x16x32_bf16 v[56:59], v[136:139], v[144:147], v[56:59]
	v_mfma_f32_16x16x32_bf16 v[52:55], v[128:131], v[152:155], v[52:55]
	v_mfma_f32_16x16x32_bf16 v[40:43], v[136:139], v[152:155], v[40:43]
	v_mfma_f32_16x16x32_bf16 v[36:39], v[128:131], v[160:163], v[36:39]
	v_mfma_f32_16x16x32_bf16 v[16:19], v[136:139], v[160:163], v[16:19]
	v_mfma_f32_16x16x32_bf16 v[12:15], v[128:131], v[168:171], v[12:15]
	v_mfma_f32_16x16x32_bf16 v[0:3], v[136:139], v[168:171], v[0:3]
	v_mfma_f32_16x16x32_bf16 v[60:63], v[132:135], v[148:151], v[60:63]
	v_mfma_f32_16x16x32_bf16 v[56:59], v[140:143], v[148:151], v[56:59]
	v_mfma_f32_16x16x32_bf16 v[52:55], v[132:135], v[156:159], v[52:55]
	v_mfma_f32_16x16x32_bf16 v[40:43], v[140:143], v[156:159], v[40:43]
	v_mfma_f32_16x16x32_bf16 v[36:39], v[132:135], v[164:167], v[36:39]
	v_mfma_f32_16x16x32_bf16 v[16:19], v[140:143], v[164:167], v[16:19]
	v_mfma_f32_16x16x32_bf16 v[12:15], v[132:135], v[172:175], v[12:15]
	v_mfma_f32_16x16x32_bf16 v[0:3], v[140:143], v[172:175], v[0:3]
	s_barrier
	s_add_u32 s78, s78, s46
	s_addc_u32 s79, s79, 0
	s_add_u32 vcc_lo, s78, 0x80
	s_addc_u32 vcc_hi, s79, 0
	s_add_i32 s82, s95, s27
	s_mov_b32 m0, s82
	s_nop 0
	global_load_lds_dwordx4 v178, s[78:79]
	s_add_i32 m0, s82, 0x2000
	s_nop 0
	global_load_lds_dwordx4 v186, s[78:79]
	s_waitcnt vmcnt(6)
	s_barrier
; #define PG8_STAGE(bufoff, gbase, voff) do { _Pragma("unroll") for (int _i = 0; _i < 2; ++_i) \
;         __builtin_amdgcn_global_load_lds((const unsigned*)((const char*)(gbase) + (voff)[_i]), (LAS unsigned*)(lds + (bufoff) + ldsw + _i * 8192), 16, 0, 0); } while (0)
; #define PG8_LDA(dst, b, h) do { _Pragma("unroll") for (int m = 0; m < 4; ++m) _Pragma("unroll") for (int k = 0; k < 2; ++k) dst[m][k] = *(const LAS bf16x8*)(lds + PG8_SA(b, h) + aoff + m * 2048 + k * 1024); } while (0)
; #define PG8_LDB(dst, b, h) do { _Pragma("unroll") for (int n = 0; n < 2; ++n) _Pragma("unroll") for (int k = 0; k < 2; ++k) dst[n][k] = *(const LAS bf16x8*)(lds + PG8_SB(b, h) + boff + n * 2048 + k * 1024); } while (0)
; #define PG8_MMA(ai, bj, At, Bt) do { __builtin_amdgcn_s_setprio(1); _Pragma("unroll") for (int m = 0; m < 4; ++m) _Pragma("unroll") for (int n = 0; n < 2; ++n) _Pragma("unroll") for (int k = 0; k < 2; ++k) \
;         acc[ai][bj][m][n] = __builtin_amdgcn_mfma_f32_16x16x32_bf16(Bt[n][k], At[m][k], acc[ai][bj][m][n], 0, 0, 0); __builtin_amdgcn_s_setprio(0); } while (0)
; #define PG8_WAIT_V(n) asm volatile("s_waitcnt vmcnt(" #n ")" ::: "memory")
; #define PG8_WAIT_L(n) asm volatile("s_waitcnt lgkmcnt(" #n ")" ::: "memory")
; #define PG8_BAR __builtin_amdgcn_s_barrier()
; #define PG8_SCHED __builtin_amdgcn_sched_barrier(0)
; template <class F>
; DI void gemm_phase(const int tid, LAS unsigned char* lds, const bf16_t* Ap, int lda, const bf16_t* Bp, int ldb, int M, int N, int K, int G, int c, bool direct, const F& E) {
;     ...
;             PG8_WAIT_V(6); PG8_BAR; PG8_MMA(1, 1, At, B1); PG8_BAR;
;             PG8_LDB(B0, 1, 0); PG8_SCHED; PG8_LDA(At, 1, 0); PG8_STAGE(PG8_SA(0, 1), a2 + hsA, voffA);
;             PG8_WAIT_L(8); PG8_BAR; PG8_WAIT_L(0); PG8_MMA(0, 0, At, B0); PG8_BAR; PG8_SCHED;
;             PG8_LDB(B1, 1, 1); PG8_STAGE(PG8_SB(1, 0), b3, voffB);
;             PG8_BAR; PG8_WAIT_L(0); PG8_MMA(0, 1, At, B1); PG8_BAR;
;             PG8_LDA(At, 1, 1); PG8_STAGE(PG8_SA(1, 0), a3, voffA);
	v_mfma_f32_16x16x32_bf16 v[48:51], v[208:211], v[144:147], v[48:51]
	v_mfma_f32_16x16x32_bf16 v[44:47], v[216:219], v[144:147], v[44:47]
	v_mfma_f32_16x16x32_bf16 v[24:27], v[208:211], v[152:155], v[24:27]
	v_mfma_f32_16x16x32_bf16 v[20:23], v[216:219], v[152:155], v[20:23]
	v_mfma_f32_16x16x32_bf16 v[28:31], v[208:211], v[160:163], v[28:31]
	v_mfma_f32_16x16x32_bf16 v[32:35], v[216:219], v[160:163], v[32:35]
	v_mfma_f32_16x16x32_bf16 v[8:11], v[208:211], v[168:171], v[8:11]
	v_mfma_f32_16x16x32_bf16 v[4:7], v[216:219], v[168:171], v[4:7]
	v_mfma_f32_16x16x32_bf16 v[48:51], v[212:215], v[148:151], v[48:51]
	v_mfma_f32_16x16x32_bf16 v[44:47], v[220:223], v[148:151], v[44:47]
	v_mfma_f32_16x16x32_bf16 v[24:27], v[212:215], v[156:159], v[24:27]
	v_mfma_f32_16x16x32_bf16 v[20:23], v[220:223], v[156:159], v[20:23]
	v_mfma_f32_16x16x32_bf16 v[28:31], v[212:215], v[164:167], v[28:31]
	v_mfma_f32_16x16x32_bf16 v[32:35], v[220:223], v[164:167], v[32:35]
	v_mfma_f32_16x16x32_bf16 v[8:11], v[212:215], v[172:175], v[8:11]
	v_mfma_f32_16x16x32_bf16 v[4:7], v[220:223], v[172:175], v[4:7]
	s_add_i32 s78, 0, 0x18000
	v_add_u32_e32 v140, s78, v189
	s_barrier
	ds_read_b128 v[128:131], v140
	ds_read_b128 v[132:135], v140 offset:1024
	ds_read_b128 v[136:139], v140 offset:2048
	ds_read_b128 v[140:143], v140 offset:3072
	s_add_u32 s76, s76, s24
	s_addc_u32 s77, s77, 0
	s_mov_b32 m0, s60
	ds_read_b128 v[144:147], v197 offset:32768
	ds_read_b128 v[148:151], v197 offset:33792
	ds_read_b128 v[152:155], v197 offset:34816
	ds_read_b128 v[156:159], v197 offset:35840
	ds_read_b128 v[160:163], v197 offset:36864
	ds_read_b128 v[164:167], v197 offset:37888
	ds_read_b128 v[168:171], v197 offset:38912
	ds_read_b128 v[172:175], v197 offset:39936
	global_load_lds_dwordx4 v176, s[76:77]
	s_mov_b32 m0, s61
	s_nop 0
	global_load_lds_dwordx4 v184, s[76:77]
	s_waitcnt lgkmcnt(8)
	s_barrier
	s_waitcnt lgkmcnt(0)
	s_waitcnt lgkmcnt(0)
	v_mfma_f32_16x16x32_bf16 v[124:127], v[128:131], v[144:147], v[124:127]
	v_mfma_f32_16x16x32_bf16 v[120:123], v[136:139], v[144:147], v[120:123]
	v_mfma_f32_16x16x32_bf16 v[116:119], v[128:131], v[152:155], v[116:119]
	v_mfma_f32_16x16x32_bf16 v[104:107], v[136:139], v[152:155], v[104:107]
	v_mfma_f32_16x16x32_bf16 v[100:103], v[128:131], v[160:163], v[100:103]
	v_mfma_f32_16x16x32_bf16 v[88:91], v[136:139], v[160:163], v[88:91]
	v_mfma_f32_16x16x32_bf16 v[84:87], v[128:131], v[168:171], v[84:87]
	v_mfma_f32_16x16x32_bf16 v[72:75], v[136:139], v[168:171], v[72:75]
	v_mfma_f32_16x16x32_bf16 v[124:127], v[132:135], v[148:151], v[124:127]
	v_mfma_f32_16x16x32_bf16 v[120:123], v[140:143], v[148:151], v[120:123]
	v_mfma_f32_16x16x32_bf16 v[116:119], v[132:135], v[156:159], v[116:119]
	v_mfma_f32_16x16x32_bf16 v[104:107], v[140:143], v[156:159], v[104:107]
	v_mfma_f32_16x16x32_bf16 v[100:103], v[132:135], v[164:167], v[100:103]
	v_mfma_f32_16x16x32_bf16 v[88:91], v[140:143], v[164:167], v[88:91]
	v_mfma_f32_16x16x32_bf16 v[84:87], v[132:135], v[172:175], v[84:87]
	v_mfma_f32_16x16x32_bf16 v[72:75], v[140:143], v[172:175], v[72:75]
	s_barrier
	s_add_i32 s76, 0, 0x1c000
	s_add_i32 s77, s78, s27
	v_add_u32_e32 v180, s76, v189
	s_mov_b32 m0, s77
	ds_read_b128 v[208:211], v180
	ds_read_b128 v[212:215], v180 offset:1024
	ds_read_b128 v[216:219], v180 offset:2048
	ds_read_b128 v[220:223], v180 offset:3072
	global_load_lds_dwordx4 v178, s[98:99]
	s_add_i32 m0, s77, 0x2000
	s_nop 0
	global_load_lds_dwordx4 v186, s[98:99]
	s_barrier
	s_waitcnt lgkmcnt(0)
	s_waitcnt lgkmcnt(0)
	v_mfma_f32_16x16x32_bf16 v[112:115], v[208:211], v[144:147], v[112:115]
	v_mfma_f32_16x16x32_bf16 v[108:111], v[216:219], v[144:147], v[108:111]
	v_mfma_f32_16x16x32_bf16 v[96:99], v[208:211], v[152:155], v[96:99]
	v_mfma_f32_16x16x32_bf16 v[92:95], v[216:219], v[152:155], v[92:95]
	v_mfma_f32_16x16x32_bf16 v[80:83], v[208:211], v[160:163], v[80:83]
	v_mfma_f32_16x16x32_bf16 v[76:79], v[216:219], v[160:163], v[76:79]
	v_mfma_f32_16x16x32_bf16 v[68:71], v[208:211], v[168:171], v[68:71]
	v_mfma_f32_16x16x32_bf16 v[64:67], v[216:219], v[168:171], v[64:67]
	v_mfma_f32_16x16x32_bf16 v[112:115], v[212:215], v[148:151], v[112:115]
	v_mfma_f32_16x16x32_bf16 v[108:111], v[220:223], v[148:151], v[108:111]
	v_mfma_f32_16x16x32_bf16 v[96:99], v[212:215], v[156:159], v[96:99]
	v_mfma_f32_16x16x32_bf16 v[92:95], v[220:223], v[156:159], v[92:95]
	v_mfma_f32_16x16x32_bf16 v[80:83], v[212:215], v[164:167], v[80:83]
	v_mfma_f32_16x16x32_bf16 v[76:79], v[220:223], v[164:167], v[76:79]
	v_mfma_f32_16x16x32_bf16 v[68:71], v[212:215], v[172:175], v[68:71]
	v_mfma_f32_16x16x32_bf16 v[64:67], v[220:223], v[172:175], v[64:67]
	s_mov_b32 m0, s62
	s_barrier
	ds_read_b128 v[144:147], v197 offset:49152
	ds_read_b128 v[148:151], v197 offset:50176
	ds_read_b128 v[152:155], v197 offset:51200
	ds_read_b128 v[156:159], v197 offset:52224
	ds_read_b128 v[160:163], v197 offset:53248
	ds_read_b128 v[164:167], v197 offset:54272
	ds_read_b128 v[168:171], v197 offset:55296
	ds_read_b128 v[172:175], v197 offset:56320
	global_load_lds_dwordx4 v176, s[100:101]
	s_mov_b32 m0, s63
	s_nop 0
	global_load_lds_dwordx4 v184, s[100:101]
	s_barrier
; #define PG8_STAGE(bufoff, gbase, voff) do { _Pragma("unroll") for (int _i = 0; _i < 2; ++_i) \
;         __builtin_amdgcn_global_load_lds((const unsigned*)((const char*)(gbase) + (voff)[_i]), (LAS unsigned*)(lds + (bufoff) + ldsw + _i * 8192), 16, 0, 0); } while (0)
; #define PG8_LDA(dst, b, h) do { _Pragma("unroll") for (int m = 0; m < 4; ++m) _Pragma("unroll") for (int k = 0; k < 2; ++k) dst[m][k] = *(const LAS bf16x8*)(lds + PG8_SA(b, h) + aoff + m * 2048 + k * 1024); } while (0)
; #define PG8_LDB(dst, b, h) do { _Pragma("unroll") for (int n = 0; n < 2; ++n) _Pragma("unroll") for (int k = 0; k < 2; ++k) dst[n][k] = *(const LAS bf16x8*)(lds + PG8_SB(b, h) + boff + n * 2048 + k * 1024); } while (0)
; #define PG8_WAIT_V(n) asm volatile("s_waitcnt vmcnt(" #n ")" ::: "memory")
; #define PG8_WAIT_L(n) asm volatile("s_waitcnt lgkmcnt(" #n ")" ::: "memory")
; #define PG8_BAR __builtin_amdgcn_s_barrier()
; #define PG8_SCHED __builtin_amdgcn_sched_barrier(0)
; template <class F>
; DI void gemm_phase(const int tid, LAS unsigned char* lds, const bf16_t* Ap, int lda, const bf16_t* Bp, int ldb, int M, int N, int K, int G, int c, bool direct, const F& E) {
;     ...
;             PG8_WAIT_L(8); PG8_BAR; PG8_WAIT_L(0); PG8_MMA(0, 0, At, B0); PG8_BAR; PG8_SCHED;
;             PG8_LDB(B1, 1, 1); PG8_STAGE(PG8_SB(1, 0), b3, voffB);
;             PG8_BAR; PG8_WAIT_L(0); PG8_MMA(0, 1, At, B1); PG8_BAR;
;             PG8_LDA(At, 1, 1); PG8_STAGE(PG8_SA(1, 0), a3, voffA);
;             PG8_BAR; PG8_WAIT_L(0); PG8_MMA(1, 0, At, B0); PG8_BAR; PG8_SCHED;
;             PG8_STAGE(PG8_SB(1, 1), b3 + hsB, voffB);
;             PG8_WAIT_V(6); PG8_BAR; PG8_MMA(1, 1, At, B1); PG8_BAR;
;         }
;         if (E.kind == 7  ) E.fused(acc, cur.pm, cur.pn, wr, wc, fr, fq);
; DI void Epi::fused(const f32x4 (&acc)[2][2][4][2], int pm, int pn, int wr, int wc, int fr, int fq) const {
;     ...
;         const int ncol = pn * 256 + bj * 128 + wc * 32 + 8 * fq, j0 = (ncol >> 3) * 4;
;         const f32x4 wa0 = *(const f32x4*)(E.cf0 + j0), wa1 = *(const f32x4*)(E.cf0 + FF2 + j0), wa2 = *(const f32x4*)(E.cf0 + 2 * FF2 + j0);
;         const f32x4 wb0 = *(const f32x4*)(E.cf0 + FFH + j0), wb1 = *(const f32x4*)(E.cf0 + FF2 + FFH + j0), wb2 = *(const f32x4*)(E.cf0 + 2 * FF2 + FFH + j0);
;         const f32x4 ba = *(const f32x4*)(E.cf1 + j0), bb = *(const f32x4*)(E.cf1 + FFH + j0);
	s_waitcnt lgkmcnt(0)
	s_waitcnt lgkmcnt(0)
	v_mfma_f32_16x16x32_bf16 v[60:63], v[128:131], v[144:147], v[60:63]
	v_mfma_f32_16x16x32_bf16 v[56:59], v[136:139], v[144:147], v[56:59]
	v_mfma_f32_16x16x32_bf16 v[52:55], v[128:131], v[152:155], v[52:55]
	v_mfma_f32_16x16x32_bf16 v[40:43], v[136:139], v[152:155], v[40:43]
	v_mfma_f32_16x16x32_bf16 v[36:39], v[128:131], v[160:163], v[36:39]
	v_mfma_f32_16x16x32_bf16 v[16:19], v[136:139], v[160:163], v[16:19]
	v_mfma_f32_16x16x32_bf16 v[12:15], v[128:131], v[168:171], v[12:15]
	v_mfma_f32_16x16x32_bf16 v[0:3], v[136:139], v[168:171], v[0:3]
	v_mfma_f32_16x16x32_bf16 v[60:63], v[132:135], v[148:151], v[60:63]
	v_mfma_f32_16x16x32_bf16 v[56:59], v[140:143], v[148:151], v[56:59]
	v_mfma_f32_16x16x32_bf16 v[52:55], v[132:135], v[156:159], v[52:55]
	v_mfma_f32_16x16x32_bf16 v[40:43], v[140:143], v[156:159], v[40:43]
	v_mfma_f32_16x16x32_bf16 v[36:39], v[132:135], v[164:167], v[36:39]
	v_mfma_f32_16x16x32_bf16 v[16:19], v[140:143], v[164:167], v[16:19]
	v_mfma_f32_16x16x32_bf16 v[12:15], v[132:135], v[172:175], v[12:15]
	v_mfma_f32_16x16x32_bf16 v[0:3], v[140:143], v[172:175], v[0:3]
	s_barrier
	s_add_i32 s76, s76, s27
	s_mov_b32 m0, s76
	s_nop 0
	global_load_lds_dwordx4 v178, vcc
	s_add_i32 m0, s76, 0x2000
	s_nop 0
	global_load_lds_dwordx4 v186, vcc
	s_waitcnt vmcnt(6)
	s_barrier
	v_mfma_f32_16x16x32_bf16 v[48:51], v[208:211], v[144:147], v[48:51]
	v_mfma_f32_16x16x32_bf16 v[44:47], v[216:219], v[144:147], v[44:47]
	v_mfma_f32_16x16x32_bf16 v[24:27], v[208:211], v[152:155], v[24:27]
	v_mfma_f32_16x16x32_bf16 v[20:23], v[216:219], v[152:155], v[20:23]
	v_mfma_f32_16x16x32_bf16 v[28:31], v[208:211], v[160:163], v[28:31]
	v_mfma_f32_16x16x32_bf16 v[32:35], v[216:219], v[160:163], v[32:35]
	v_mfma_f32_16x16x32_bf16 v[8:11], v[208:211], v[168:171], v[8:11]
	v_mfma_f32_16x16x32_bf16 v[4:7], v[216:219], v[168:171], v[4:7]
	v_mfma_f32_16x16x32_bf16 v[48:51], v[212:215], v[148:151], v[48:51]
	v_mfma_f32_16x16x32_bf16 v[44:47], v[220:223], v[148:151], v[44:47]
	v_mfma_f32_16x16x32_bf16 v[24:27], v[212:215], v[156:159], v[24:27]
	v_mfma_f32_16x16x32_bf16 v[20:23], v[220:223], v[156:159], v[20:23]
	v_mfma_f32_16x16x32_bf16 v[28:31], v[212:215], v[164:167], v[28:31]
	v_mfma_f32_16x16x32_bf16 v[32:35], v[220:223], v[164:167], v[32:35]
	v_mfma_f32_16x16x32_bf16 v[8:11], v[212:215], v[172:175], v[8:11]
	v_mfma_f32_16x16x32_bf16 v[4:7], v[220:223], v[172:175], v[4:7]
	s_add_u32 s74, s74, 0x100
	s_addc_u32 s75, s75, 0
	s_add_u32 s71, s71, 0x100
	s_addc_u32 s80, s80, 0
	s_cmp_ge_u32 s81, s26
	s_mov_b32 s76, s81
	s_barrier
	s_cbranch_scc0 .LBB0_657
	s_cmp_eq_u32 s92, 0
	s_cbranch_scc1 .Labin_epi
.Labin_back:
	s_mov_b64 s[76:77], -1
	s_mov_b64 s[74:75], 0
	s_cmp_lt_i32 s92, 3
	s_mov_b64 s[78:79], 0
	s_cbranch_scc1 .LBB0_688
	s_cmp_gt_i32 s92, 6
	s_mov_b64 s[78:79], -1
	s_cbranch_scc0 .LBB0_685
	s_mov_b32 s98, 0xbfb8aa3b
	s_mov_b32 s99, 0xbfb8aa3b
	s_mov_b32 s100, 1.0
	s_mov_b32 s101, 1.0
	v_lshl_or_b32 v240, s70, 8, v194
	v_mov_b32_e32 v241, 0
	s_lshl_b32 s71, s36, 8
	v_readlane_b32 s76, v255, 16
	s_nop 3
	s_add_i32 s71, s71, s76
	v_or_b32_e32 v199, s71, v188
	v_lshlrev_b32_e32 v238, 1, v240
	v_mov_b32_e32 v239, 0
	v_lshl_add_u64 v[136:137], s[22:23], 0, v[238:239]
	global_load_dwordx4 v[136:139], v[136:137], off
	v_readlane_b32 s76, v254, 54
	v_readlane_b32 s77, v254, 55
	s_nop 1
	v_lshl_add_u64 v[140:141], s[76:77], 0, v[238:239]
	global_load_dwordx4 v[140:143], v[140:141], off
	v_readlane_b32 s76, v254, 56
	v_readlane_b32 s77, v254, 57
	s_nop 1
	v_lshl_add_u64 v[152:153], s[76:77], 0, v[238:239]
	global_load_dwordx4 v[152:155], v[152:153], off
	v_readlane_b32 s76, v255, 4
	v_readlane_b32 s77, v255, 5
	s_nop 1
	v_lshl_add_u64 v[128:129], s[76:77], 0, v[238:239]
	global_load_dwordx4 v[128:131], v[128:129], off
	v_readlane_b32 s76, v255, 6
	v_readlane_b32 s77, v255, 7
	s_nop 1
	v_lshl_add_u64 v[132:133], s[76:77], 0, v[238:239]
	global_load_dwordx4 v[132:135], v[132:133], off
	v_readlane_b32 s76, v255, 8
	v_readlane_b32 s77, v255, 9
	s_nop 1
	v_lshl_add_u64 v[144:145], s[76:77], 0, v[238:239]
	global_load_dwordx4 v[144:147], v[144:145], off
	v_readlane_b32 s76, v254, 49
	v_readlane_b32 s77, v254, 50
	s_nop 1
	v_lshl_add_u64 v[156:157], s[76:77], 0, v[238:239]
	global_load_dwordx4 v[156:159], v[156:157], off
	v_lshl_add_u64 v[148:149], s[72:73], 0, v[238:239]
	global_load_dwordx4 v[148:151], v[148:149], off
	v_mov_b32_e32 v228, v199
	v_mov_b64_e32 v[224:225], s[12:13]
	s_movk_i32 s80, 0x1600
	v_mad_i64_i32 v[224:225], s[78:79], v228, s80, v[224:225]
	v_mov_b32_e32 v228, v240
	v_mov_b32_e32 v229, 0
	v_lshl_add_u64 v[224:225], v[228:229], 0, v[224:225]
	s_waitcnt vmcnt(0)
; DI float silu_fast(float x) { return x * __builtin_amdgcn_rcpf(1.f + __expf(-x)); }
; template <int CTRL> DI float dppf(float v) { return __builtin_bit_cast(float, __builtin_amdgcn_update_dpp(0, __builtin_bit_cast(int, v), CTRL, 0xf, 0xf, true)); }
; DI void Epi::fused(const f32x4 (&acc)[2][2][4][2], int pm, int pn, int wr, int wc, int fr, int fq) const {
;     ...
;             for (int m = 0; m < 4; ++m) {
;                 const f32x4 ca = acc[ai][bj][m][0], cb = acc[ai][bj][m][1];
;                 const int row = pm * 256 + ai * 128 + wr * 64 + m * 16 + fr;
;                 float o[4];
; #pragma unroll
;                 for (int e = 0; e < 4; ++e) {
;                     const float a1 = dppf<0x111>(ca[e]) + dppf<0x10F>(pa[e]), a2 = dppf<0x112>(ca[e]) + dppf<0x10E>(pa[e]);
;                     const float b1 = dppf<0x111>(cb[e]) + dppf<0x10F>(pb[e]), b2 = dppf<0x112>(cb[e]) + dppf<0x10E>(pb[e]);
;                     const float ya = fmaf(wa0[e], a2, fmaf(wa1[e], a1, fmaf(wa2[e], ca[e], ba[e])));
;                     const float yb = fmaf(wb0[e], b2, fmaf(wb1[e], b1, fmaf(wb2[e], cb[e], bb[e])));
;                     o[e] = silu_fast(ya) * yb; }
;                 if (m > 0 || fr >= 2) { u32x2 w; w.x = pk2(o[0], o[1]); w.y = pk2(o[2], o[3]); *(u32x2*)(E.d0 + (size_t)row * FFH + j0) = w; }
;                 if ((m == 0 && fr < 2) || (m == 3 && fr >= 14)) { float* hb = E.f0 + ((size_t)(row >> 6) * 4 + (m == 0 ? fr : fr - 12)) * FF2 + ncol; *(f32x4*)hb = ca; *(f32x4*)(hb + 4) = cb; }
;                 pa = ca; pb = cb;
	v_fma_f32 v160, v152, v124, v156
	v_fma_f32 v161, v153, v125, v157
	v_fma_f32 v162, v154, v126, v158
	v_fma_f32 v163, v155, v127, v159
	v_fma_f32 v164, v144, v120, v148
	v_fma_f32 v165, v145, v121, v149
	v_fma_f32 v166, v146, v122, v150
	v_fma_f32 v167, v147, v123, v151
	v_fmac_f32_dpp v160, v124, v140 row_shr:1 row_mask:0xf bank_mask:0xf
	v_fmac_f32_dpp v161, v125, v141 row_shr:1 row_mask:0xf bank_mask:0xf
	v_fmac_f32_dpp v162, v126, v142 row_shr:1 row_mask:0xf bank_mask:0xf
	v_fmac_f32_dpp v163, v127, v143 row_shr:1 row_mask:0xf bank_mask:0xf
	v_fmac_f32_dpp v164, v120, v132 row_shr:1 row_mask:0xf bank_mask:0xf
	v_fmac_f32_dpp v165, v121, v133 row_shr:1 row_mask:0xf bank_mask:0xf
	v_fmac_f32_dpp v166, v122, v134 row_shr:1 row_mask:0xf bank_mask:0xf
	v_fmac_f32_dpp v167, v123, v135 row_shr:1 row_mask:0xf bank_mask:0xf
	v_fmac_f32_dpp v160, v124, v136 row_shr:2 row_mask:0xf bank_mask:0xf
	v_fmac_f32_dpp v161, v125, v137 row_shr:2 row_mask:0xf bank_mask:0xf
	v_fmac_f32_dpp v162, v126, v138 row_shr:2 row_mask:0xf bank_mask:0xf
	v_fmac_f32_dpp v163, v127, v139 row_shr:2 row_mask:0xf bank_mask:0xf
	v_fmac_f32_dpp v164, v120, v128 row_shr:2 row_mask:0xf bank_mask:0xf
	v_fmac_f32_dpp v165, v121, v129 row_shr:2 row_mask:0xf bank_mask:0xf
	v_fmac_f32_dpp v166, v122, v130 row_shr:2 row_mask:0xf bank_mask:0xf
	v_fmac_f32_dpp v167, v123, v131 row_shr:2 row_mask:0xf bank_mask:0xf
	v_pk_mul_f32 v[168:169], v[160:161], s[98:99]
	v_pk_mul_f32 v[170:171], v[162:163], s[98:99]
	v_exp_f32_e32 v168, v168
	v_exp_f32_e32 v169, v169
	v_exp_f32_e32 v170, v170
	v_exp_f32_e32 v171, v171
	v_pk_add_f32 v[168:169], v[168:169], s[100:101]
	v_pk_add_f32 v[170:171], v[170:171], s[100:101]
	v_rcp_f32_e32 v168, v168
	v_rcp_f32_e32 v169, v169
	v_rcp_f32_e32 v170, v170
	v_rcp_f32_e32 v171, v171
	v_mov_b64_e32 v[174:175], v[224:225]
	v_mul_f32_e32 v160, v160, v168
	v_mul_f32_e32 v161, v161, v169
	v_mul_f32_e32 v162, v162, v170
	v_mul_f32_e32 v163, v163, v171
	v_mul_f32_e32 v160, v164, v160
	v_mul_f32_e32 v161, v165, v161
	v_mul_f32_e32 v162, v166, v162
	v_mul_f32_e32 v163, v167, v163
	v_cvt_pk_bf16_f32 v172, v160, v161
	v_cvt_pk_bf16_f32 v173, v162, v163
	s_and_saveexec_b64 s[76:77], s[38:39]
	global_store_dwordx2 v[174:175], v[172:173], off
	s_or_b64 exec, exec, s[76:77]
	s_ashr_i32 s80, s71, 6
	s_lshl_b32 s80, s80, 2
	v_add_u32_e32 v226, s80, v188
	v_mov_b64_e32 v[174:175], s[8:9]
	s_movk_i32 s80, 0x5800
	v_mad_i64_i32 v[174:175], s[78:79], v226, s80, v[174:175]
	v_lshl_add_u64 v[174:175], v[228:229], 2, v[174:175]
	s_and_saveexec_b64 s[76:77], s[40:41]
	global_store_dwordx4 v[174:175], v[124:127], off
	global_store_dwordx4 v[174:175], v[120:123], off offset:16
	s_or_b64 exec, exec, s[76:77]
	v_fma_f32 v208, v152, v116, v156
	v_fma_f32 v209, v153, v117, v157
	v_fma_f32 v210, v154, v118, v158
	v_fma_f32 v211, v155, v119, v159
	v_fma_f32 v212, v144, v104, v148
	v_fma_f32 v213, v145, v105, v149
	v_fma_f32 v214, v146, v106, v150
	v_fma_f32 v215, v147, v107, v151
	v_fmac_f32_dpp v208, v116, v140 row_shr:1 row_mask:0xf bank_mask:0xf
	v_fmac_f32_dpp v209, v117, v141 row_shr:1 row_mask:0xf bank_mask:0xf
	v_fmac_f32_dpp v210, v118, v142 row_shr:1 row_mask:0xf bank_mask:0xf
	v_fmac_f32_dpp v211, v119, v143 row_shr:1 row_mask:0xf bank_mask:0xf
	v_fmac_f32_dpp v212, v104, v132 row_shr:1 row_mask:0xf bank_mask:0xf
	v_fmac_f32_dpp v213, v105, v133 row_shr:1 row_mask:0xf bank_mask:0xf
	v_fmac_f32_dpp v214, v106, v134 row_shr:1 row_mask:0xf bank_mask:0xf
	v_fmac_f32_dpp v215, v107, v135 row_shr:1 row_mask:0xf bank_mask:0xf
	v_fmac_f32_dpp v208, v124, v140 row_shl:15 row_mask:0xf bank_mask:0xf
	v_fmac_f32_dpp v209, v125, v141 row_shl:15 row_mask:0xf bank_mask:0xf
	v_fmac_f32_dpp v210, v126, v142 row_shl:15 row_mask:0xf bank_mask:0xf
	v_fmac_f32_dpp v211, v127, v143 row_shl:15 row_mask:0xf bank_mask:0xf
	v_fmac_f32_dpp v212, v120, v132 row_shl:15 row_mask:0xf bank_mask:0xf
	v_fmac_f32_dpp v213, v121, v133 row_shl:15 row_mask:0xf bank_mask:0xf
	v_fmac_f32_dpp v214, v122, v134 row_shl:15 row_mask:0xf bank_mask:0xf
	v_fmac_f32_dpp v215, v123, v135 row_shl:15 row_mask:0xf bank_mask:0xf
	v_fmac_f32_dpp v208, v116, v136 row_shr:2 row_mask:0xf bank_mask:0xf
	v_fmac_f32_dpp v209, v117, v137 row_shr:2 row_mask:0xf bank_mask:0xf
	v_fmac_f32_dpp v210, v118, v138 row_shr:2 row_mask:0xf bank_mask:0xf
	v_fmac_f32_dpp v211, v119, v139 row_shr:2 row_mask:0xf bank_mask:0xf
	v_fmac_f32_dpp v212, v104, v128 row_shr:2 row_mask:0xf bank_mask:0xf
	v_fmac_f32_dpp v213, v105, v129 row_shr:2 row_mask:0xf bank_mask:0xf
	v_fmac_f32_dpp v214, v106, v130 row_shr:2 row_mask:0xf bank_mask:0xf
	v_fmac_f32_dpp v215, v107, v131 row_shr:2 row_mask:0xf bank_mask:0xf
	v_fmac_f32_dpp v208, v124, v136 row_shl:14 row_mask:0xf bank_mask:0xf
	v_fmac_f32_dpp v209, v125, v137 row_shl:14 row_mask:0xf bank_mask:0xf
	v_fmac_f32_dpp v210, v126, v138 row_shl:14 row_mask:0xf bank_mask:0xf
	v_fmac_f32_dpp v211, v127, v139 row_shl:14 row_mask:0xf bank_mask:0xf
	v_fmac_f32_dpp v212, v120, v128 row_shl:14 row_mask:0xf bank_mask:0xf
	v_fmac_f32_dpp v213, v121, v129 row_shl:14 row_mask:0xf bank_mask:0xf
	v_fmac_f32_dpp v214, v122, v130 row_shl:14 row_mask:0xf bank_mask:0xf
	v_fmac_f32_dpp v215, v123, v131 row_shl:14 row_mask:0xf bank_mask:0xf
	v_pk_mul_f32 v[216:217], v[208:209], s[98:99]
	v_pk_mul_f32 v[218:219], v[210:211], s[98:99]
	v_exp_f32_e32 v216, v216
	v_exp_f32_e32 v217, v217
	v_exp_f32_e32 v218, v218
	v_exp_f32_e32 v219, v219
	v_pk_add_f32 v[216:217], v[216:217], s[100:101]
	v_pk_add_f32 v[218:219], v[218:219], s[100:101]
	v_rcp_f32_e32 v216, v216
	v_rcp_f32_e32 v217, v217
	v_rcp_f32_e32 v218, v218
	v_rcp_f32_e32 v219, v219
; DI float silu_fast(float x) { return x * __builtin_amdgcn_rcpf(1.f + __expf(-x)); }
; template <int CTRL> DI float dppf(float v) { return __builtin_bit_cast(float, __builtin_amdgcn_update_dpp(0, __builtin_bit_cast(int, v), CTRL, 0xf, 0xf, true)); }
; DI void Epi::fused(const f32x4 (&acc)[2][2][4][2], int pm, int pn, int wr, int wc, int fr, int fq) const {
;     ...
;             for (int m = 0; m < 4; ++m) {
;                 const f32x4 ca = acc[ai][bj][m][0], cb = acc[ai][bj][m][1];
;                 const int row = pm * 256 + ai * 128 + wr * 64 + m * 16 + fr;
;                 float o[4];
; #pragma unroll
;                 for (int e = 0; e < 4; ++e) {
;                     const float a1 = dppf<0x111>(ca[e]) + dppf<0x10F>(pa[e]), a2 = dppf<0x112>(ca[e]) + dppf<0x10E>(pa[e]);
;                     const float b1 = dppf<0x111>(cb[e]) + dppf<0x10F>(pb[e]), b2 = dppf<0x112>(cb[e]) + dppf<0x10E>(pb[e]);
;                     const float ya = fmaf(wa0[e], a2, fmaf(wa1[e], a1, fmaf(wa2[e], ca[e], ba[e])));
;                     const float yb = fmaf(wb0[e], b2, fmaf(wb1[e], b1, fmaf(wb2[e], cb[e], bb[e])));
;                     o[e] = silu_fast(ya) * yb; }
;                 if (m > 0 || fr >= 2) { u32x2 w; w.x = pk2(o[0], o[1]); w.y = pk2(o[2], o[3]); *(u32x2*)(E.d0 + (size_t)row * FFH + j0) = w; }
	s_mov_b32 s80, 0x16000
	s_mov_b32 s81, 0
	v_lshl_add_u64 v[222:223], v[224:225], 0, s[80:81]
	v_mul_f32_e32 v208, v208, v216
	v_mul_f32_e32 v209, v209, v217
	v_mul_f32_e32 v210, v210, v218
	v_mul_f32_e32 v211, v211, v219
	v_mul_f32_e32 v208, v212, v208
	v_mul_f32_e32 v209, v213, v209
	v_mul_f32_e32 v210, v214, v210
	v_mul_f32_e32 v211, v215, v211
	v_cvt_pk_bf16_f32 v220, v208, v209
	v_cvt_pk_bf16_f32 v221, v210, v211
	global_store_dwordx2 v[222:223], v[220:221], off
	v_fma_f32 v160, v152, v100, v156
	v_fma_f32 v161, v153, v101, v157
	v_fma_f32 v162, v154, v102, v158
	v_fma_f32 v163, v155, v103, v159
	v_fma_f32 v164, v144, v88, v148
	v_fma_f32 v165, v145, v89, v149
	v_fma_f32 v166, v146, v90, v150
	v_fma_f32 v167, v147, v91, v151
	v_fmac_f32_dpp v160, v100, v140 row_shr:1 row_mask:0xf bank_mask:0xf
	v_fmac_f32_dpp v161, v101, v141 row_shr:1 row_mask:0xf bank_mask:0xf
	v_fmac_f32_dpp v162, v102, v142 row_shr:1 row_mask:0xf bank_mask:0xf
	v_fmac_f32_dpp v163, v103, v143 row_shr:1 row_mask:0xf bank_mask:0xf
	v_fmac_f32_dpp v164, v88, v132 row_shr:1 row_mask:0xf bank_mask:0xf
	v_fmac_f32_dpp v165, v89, v133 row_shr:1 row_mask:0xf bank_mask:0xf
	v_fmac_f32_dpp v166, v90, v134 row_shr:1 row_mask:0xf bank_mask:0xf
	v_fmac_f32_dpp v167, v91, v135 row_shr:1 row_mask:0xf bank_mask:0xf
	v_fmac_f32_dpp v160, v116, v140 row_shl:15 row_mask:0xf bank_mask:0xf
	v_fmac_f32_dpp v161, v117, v141 row_shl:15 row_mask:0xf bank_mask:0xf
	v_fmac_f32_dpp v162, v118, v142 row_shl:15 row_mask:0xf bank_mask:0xf
	v_fmac_f32_dpp v163, v119, v143 row_shl:15 row_mask:0xf bank_mask:0xf
	v_fmac_f32_dpp v164, v104, v132 row_shl:15 row_mask:0xf bank_mask:0xf
	v_fmac_f32_dpp v165, v105, v133 row_shl:15 row_mask:0xf bank_mask:0xf
	v_fmac_f32_dpp v166, v106, v134 row_shl:15 row_mask:0xf bank_mask:0xf
	v_fmac_f32_dpp v167, v107, v135 row_shl:15 row_mask:0xf bank_mask:0xf
	v_fmac_f32_dpp v160, v100, v136 row_shr:2 row_mask:0xf bank_mask:0xf
	v_fmac_f32_dpp v161, v101, v137 row_shr:2 row_mask:0xf bank_mask:0xf
	v_fmac_f32_dpp v162, v102, v138 row_shr:2 row_mask:0xf bank_mask:0xf
	v_fmac_f32_dpp v163, v103, v139 row_shr:2 row_mask:0xf bank_mask:0xf
	v_fmac_f32_dpp v164, v88, v128 row_shr:2 row_mask:0xf bank_mask:0xf
	v_fmac_f32_dpp v165, v89, v129 row_shr:2 row_mask:0xf bank_mask:0xf
	v_fmac_f32_dpp v166, v90, v130 row_shr:2 row_mask:0xf bank_mask:0xf
	v_fmac_f32_dpp v167, v91, v131 row_shr:2 row_mask:0xf bank_mask:0xf
	v_fmac_f32_dpp v160, v116, v136 row_shl:14 row_mask:0xf bank_mask:0xf
	v_fmac_f32_dpp v161, v117, v137 row_shl:14 row_mask:0xf bank_mask:0xf
	v_fmac_f32_dpp v162, v118, v138 row_shl:14 row_mask:0xf bank_mask:0xf
	v_fmac_f32_dpp v163, v119, v139 row_shl:14 row_mask:0xf bank_mask:0xf
	v_fmac_f32_dpp v164, v104, v128 row_shl:14 row_mask:0xf bank_mask:0xf
	v_fmac_f32_dpp v165, v105, v129 row_shl:14 row_mask:0xf bank_mask:0xf
	v_fmac_f32_dpp v166, v106, v130 row_shl:14 row_mask:0xf bank_mask:0xf
	v_fmac_f32_dpp v167, v107, v131 row_shl:14 row_mask:0xf bank_mask:0xf
	v_pk_mul_f32 v[168:169], v[160:161], s[98:99]
	v_pk_mul_f32 v[170:171], v[162:163], s[98:99]
	v_exp_f32_e32 v168, v168
	v_exp_f32_e32 v169, v169
	v_exp_f32_e32 v170, v170
	v_exp_f32_e32 v171, v171
	v_pk_add_f32 v[168:169], v[168:169], s[100:101]
	v_pk_add_f32 v[170:171], v[170:171], s[100:101]
	v_rcp_f32_e32 v168, v168
	v_rcp_f32_e32 v169, v169
	v_rcp_f32_e32 v170, v170
	v_rcp_f32_e32 v171, v171
	s_mov_b32 s80, 0x2c000
	s_mov_b32 s81, 0
	v_lshl_add_u64 v[174:175], v[224:225], 0, s[80:81]
	v_mul_f32_e32 v160, v160, v168
	v_mul_f32_e32 v161, v161, v169
	v_mul_f32_e32 v162, v162, v170
	v_mul_f32_e32 v163, v163, v171
	v_mul_f32_e32 v160, v164, v160
	v_mul_f32_e32 v161, v165, v161
	v_mul_f32_e32 v162, v166, v162
	v_mul_f32_e32 v163, v167, v163
	v_cvt_pk_bf16_f32 v172, v160, v161
	v_cvt_pk_bf16_f32 v173, v162, v163
	global_store_dwordx2 v[174:175], v[172:173], off
	v_fma_f32 v208, v152, v84, v156
	v_fma_f32 v209, v153, v85, v157
	v_fma_f32 v210, v154, v86, v158
	v_fma_f32 v211, v155, v87, v159
	v_fma_f32 v212, v144, v72, v148
	v_fma_f32 v213, v145, v73, v149
	v_fma_f32 v214, v146, v74, v150
	v_fma_f32 v215, v147, v75, v151
	v_fmac_f32_dpp v208, v84, v140 row_shr:1 row_mask:0xf bank_mask:0xf
	v_fmac_f32_dpp v209, v85, v141 row_shr:1 row_mask:0xf bank_mask:0xf
	v_fmac_f32_dpp v210, v86, v142 row_shr:1 row_mask:0xf bank_mask:0xf
	v_fmac_f32_dpp v211, v87, v143 row_shr:1 row_mask:0xf bank_mask:0xf
	v_fmac_f32_dpp v212, v72, v132 row_shr:1 row_mask:0xf bank_mask:0xf
	v_fmac_f32_dpp v213, v73, v133 row_shr:1 row_mask:0xf bank_mask:0xf
	v_fmac_f32_dpp v214, v74, v134 row_shr:1 row_mask:0xf bank_mask:0xf
	v_fmac_f32_dpp v215, v75, v135 row_shr:1 row_mask:0xf bank_mask:0xf
	v_fmac_f32_dpp v208, v100, v140 row_shl:15 row_mask:0xf bank_mask:0xf
	v_fmac_f32_dpp v209, v101, v141 row_shl:15 row_mask:0xf bank_mask:0xf
	v_fmac_f32_dpp v210, v102, v142 row_shl:15 row_mask:0xf bank_mask:0xf
	v_fmac_f32_dpp v211, v103, v143 row_shl:15 row_mask:0xf bank_mask:0xf
	v_fmac_f32_dpp v212, v88, v132 row_shl:15 row_mask:0xf bank_mask:0xf
	v_fmac_f32_dpp v213, v89, v133 row_shl:15 row_mask:0xf bank_mask:0xf
	v_fmac_f32_dpp v214, v90, v134 row_shl:15 row_mask:0xf bank_mask:0xf
	v_fmac_f32_dpp v215, v91, v135 row_shl:15 row_mask:0xf bank_mask:0xf
	v_fmac_f32_dpp v208, v84, v136 row_shr:2 row_mask:0xf bank_mask:0xf
	v_fmac_f32_dpp v209, v85, v137 row_shr:2 row_mask:0xf bank_mask:0xf
	v_fmac_f32_dpp v210, v86, v138 row_shr:2 row_mask:0xf bank_mask:0xf
	v_fmac_f32_dpp v211, v87, v139 row_shr:2 row_mask:0xf bank_mask:0xf
	v_fmac_f32_dpp v212, v72, v128 row_shr:2 row_mask:0xf bank_mask:0xf
	v_fmac_f32_dpp v213, v73, v129 row_shr:2 row_mask:0xf bank_mask:0xf
; DI float silu_fast(float x) { return x * __builtin_amdgcn_rcpf(1.f + __expf(-x)); }
; template <int CTRL> DI float dppf(float v) { return __builtin_bit_cast(float, __builtin_amdgcn_update_dpp(0, __builtin_bit_cast(int, v), CTRL, 0xf, 0xf, true)); }
; DI void Epi::fused(const f32x4 (&acc)[2][2][4][2], int pm, int pn, int wr, int wc, int fr, int fq) const {
;     ...
;         const int ncol = pn * 256 + bj * 128 + wc * 32 + 8 * fq, j0 = (ncol >> 3) * 4;
;         const f32x4 wa0 = *(const f32x4*)(E.cf0 + j0), wa1 = *(const f32x4*)(E.cf0 + FF2 + j0), wa2 = *(const f32x4*)(E.cf0 + 2 * FF2 + j0);
;         const f32x4 wb0 = *(const f32x4*)(E.cf0 + FFH + j0), wb1 = *(const f32x4*)(E.cf0 + FF2 + FFH + j0), wb2 = *(const f32x4*)(E.cf0 + 2 * FF2 + FFH + j0);
;         const f32x4 ba = *(const f32x4*)(E.cf1 + j0), bb = *(const f32x4*)(E.cf1 + FFH + j0);
; #pragma unroll
;         for (int ai = 0; ai < 2; ++ai) {
;             f32x4 pa = (f32x4){0.f, 0.f, 0.f, 0.f}, pb = pa;
; #pragma unroll
;             for (int m = 0; m < 4; ++m) {
;                 const f32x4 ca = acc[ai][bj][m][0], cb = acc[ai][bj][m][1];
;                 const int row = pm * 256 + ai * 128 + wr * 64 + m * 16 + fr;
;                 float o[4];
; #pragma unroll
;                 for (int e = 0; e < 4; ++e) {
;                     const float a1 = dppf<0x111>(ca[e]) + dppf<0x10F>(pa[e]), a2 = dppf<0x112>(ca[e]) + dppf<0x10E>(pa[e]);
;                     const float b1 = dppf<0x111>(cb[e]) + dppf<0x10F>(pb[e]), b2 = dppf<0x112>(cb[e]) + dppf<0x10E>(pb[e]);
;                     const float ya = fmaf(wa0[e], a2, fmaf(wa1[e], a1, fmaf(wa2[e], ca[e], ba[e])));
;                     const float yb = fmaf(wb0[e], b2, fmaf(wb1[e], b1, fmaf(wb2[e], cb[e], bb[e])));
;                     o[e] = silu_fast(ya) * yb; }
;                 if (m > 0 || fr >= 2) { u32x2 w; w.x = pk2(o[0], o[1]); w.y = pk2(o[2], o[3]); *(u32x2*)(E.d0 + (size_t)row * FFH + j0) = w; }
;                 if ((m == 0 && fr < 2) || (m == 3 && fr >= 14)) { float* hb = E.f0 + ((size_t)(row >> 6) * 4 + (m == 0 ? fr : fr - 12)) * FF2 + ncol; *(f32x4*)hb = ca; *(f32x4*)(hb + 4) = cb; }
	v_fmac_f32_dpp v214, v74, v130 row_shr:2 row_mask:0xf bank_mask:0xf
	v_fmac_f32_dpp v215, v75, v131 row_shr:2 row_mask:0xf bank_mask:0xf
	v_fmac_f32_dpp v208, v100, v136 row_shl:14 row_mask:0xf bank_mask:0xf
	v_fmac_f32_dpp v209, v101, v137 row_shl:14 row_mask:0xf bank_mask:0xf
	v_fmac_f32_dpp v210, v102, v138 row_shl:14 row_mask:0xf bank_mask:0xf
	v_fmac_f32_dpp v211, v103, v139 row_shl:14 row_mask:0xf bank_mask:0xf
	v_fmac_f32_dpp v212, v88, v128 row_shl:14 row_mask:0xf bank_mask:0xf
	v_fmac_f32_dpp v213, v89, v129 row_shl:14 row_mask:0xf bank_mask:0xf
	v_fmac_f32_dpp v214, v90, v130 row_shl:14 row_mask:0xf bank_mask:0xf
	v_fmac_f32_dpp v215, v91, v131 row_shl:14 row_mask:0xf bank_mask:0xf
	v_pk_mul_f32 v[216:217], v[208:209], s[98:99]
	v_pk_mul_f32 v[218:219], v[210:211], s[98:99]
	v_exp_f32_e32 v216, v216
	v_exp_f32_e32 v217, v217
	v_exp_f32_e32 v218, v218
	v_exp_f32_e32 v219, v219
	v_pk_add_f32 v[216:217], v[216:217], s[100:101]
	v_pk_add_f32 v[218:219], v[218:219], s[100:101]
	v_rcp_f32_e32 v216, v216
	v_rcp_f32_e32 v217, v217
	v_rcp_f32_e32 v218, v218
	v_rcp_f32_e32 v219, v219
	s_mov_b32 s80, 0x42000
	s_mov_b32 s81, 0
	v_lshl_add_u64 v[222:223], v[224:225], 0, s[80:81]
	v_mul_f32_e32 v208, v208, v216
	v_mul_f32_e32 v209, v209, v217
	v_mul_f32_e32 v210, v210, v218
	v_mul_f32_e32 v211, v211, v219
	v_mul_f32_e32 v208, v212, v208
	v_mul_f32_e32 v209, v213, v209
	v_mul_f32_e32 v210, v214, v210
	v_mul_f32_e32 v211, v215, v211
	v_cvt_pk_bf16_f32 v220, v208, v209
	v_cvt_pk_bf16_f32 v221, v210, v211
	global_store_dwordx2 v[222:223], v[220:221], off
	s_ashr_i32 s80, s71, 6
	s_lshl_b32 s80, s80, 2
	v_add_u32_e32 v226, s80, v190
	v_mov_b64_e32 v[222:223], s[8:9]
	s_movk_i32 s80, 0x5800
	v_mad_i64_i32 v[222:223], s[78:79], v226, s80, v[222:223]
	v_lshl_add_u64 v[222:223], v[228:229], 2, v[222:223]
	s_and_saveexec_b64 s[76:77], s[42:43]
	global_store_dwordx4 v[222:223], v[84:87], off
	global_store_dwordx4 v[222:223], v[72:75], off offset:16
	s_or_b64 exec, exec, s[76:77]
	v_add_u32_e32 v238, 0x80, v240
	v_lshlrev_b32_e32 v238, 1, v238
	v_mov_b32_e32 v239, 0
	v_lshl_add_u64 v[84:85], s[22:23], 0, v[238:239]
	global_load_dwordx4 v[84:87], v[84:85], off
	v_readlane_b32 s76, v254, 54
	v_readlane_b32 s77, v254, 55
	s_nop 1
	v_lshl_add_u64 v[88:89], s[76:77], 0, v[238:239]
	global_load_dwordx4 v[88:91], v[88:89], off
	v_readlane_b32 s76, v254, 56
	v_readlane_b32 s77, v254, 57
	s_nop 1
	v_lshl_add_u64 v[100:101], s[76:77], 0, v[238:239]
	global_load_dwordx4 v[100:103], v[100:101], off
	v_readlane_b32 s76, v255, 4
	v_readlane_b32 s77, v255, 5
	s_nop 1
	v_lshl_add_u64 v[104:105], s[76:77], 0, v[238:239]
	global_load_dwordx4 v[104:107], v[104:105], off
	v_readlane_b32 s76, v255, 6
	v_readlane_b32 s77, v255, 7
	s_nop 1
	v_lshl_add_u64 v[116:117], s[76:77], 0, v[238:239]
	global_load_dwordx4 v[116:119], v[116:117], off
	v_readlane_b32 s76, v255, 8
	v_readlane_b32 s77, v255, 9
	s_nop 1
	v_lshl_add_u64 v[120:121], s[76:77], 0, v[238:239]
	global_load_dwordx4 v[120:123], v[120:121], off
	v_readlane_b32 s76, v254, 49
	v_readlane_b32 s77, v254, 50
	s_nop 1
	v_lshl_add_u64 v[124:125], s[76:77], 0, v[238:239]
	global_load_dwordx4 v[124:127], v[124:125], off
	v_lshl_add_u64 v[72:73], s[72:73], 0, v[238:239]
	global_load_dwordx4 v[72:75], v[72:73], off
	v_add_u32_e32 v228, 128, v199
	v_mov_b64_e32 v[224:225], s[12:13]
	s_movk_i32 s80, 0x1600
	v_mad_i64_i32 v[224:225], s[78:79], v228, s80, v[224:225]
	v_mov_b32_e32 v228, v240
	v_mov_b32_e32 v229, 0
	v_lshl_add_u64 v[224:225], v[228:229], 0, v[224:225]
	v_fma_f32 v160, v152, v60, v156
	v_fma_f32 v161, v153, v61, v157
	v_fma_f32 v162, v154, v62, v158
	v_fma_f32 v163, v155, v63, v159
	v_fma_f32 v164, v144, v56, v148
	v_fma_f32 v165, v145, v57, v149
	v_fma_f32 v166, v146, v58, v150
	v_fma_f32 v167, v147, v59, v151
	v_fmac_f32_dpp v160, v60, v140 row_shr:1 row_mask:0xf bank_mask:0xf
	v_fmac_f32_dpp v161, v61, v141 row_shr:1 row_mask:0xf bank_mask:0xf
	v_fmac_f32_dpp v162, v62, v142 row_shr:1 row_mask:0xf bank_mask:0xf
	v_fmac_f32_dpp v163, v63, v143 row_shr:1 row_mask:0xf bank_mask:0xf
	v_fmac_f32_dpp v164, v56, v132 row_shr:1 row_mask:0xf bank_mask:0xf
	v_fmac_f32_dpp v165, v57, v133 row_shr:1 row_mask:0xf bank_mask:0xf
	v_fmac_f32_dpp v166, v58, v134 row_shr:1 row_mask:0xf bank_mask:0xf
	v_fmac_f32_dpp v167, v59, v135 row_shr:1 row_mask:0xf bank_mask:0xf
	v_fmac_f32_dpp v160, v60, v136 row_shr:2 row_mask:0xf bank_mask:0xf
	v_fmac_f32_dpp v161, v61, v137 row_shr:2 row_mask:0xf bank_mask:0xf
	v_fmac_f32_dpp v162, v62, v138 row_shr:2 row_mask:0xf bank_mask:0xf
	v_fmac_f32_dpp v163, v63, v139 row_shr:2 row_mask:0xf bank_mask:0xf
	v_fmac_f32_dpp v164, v56, v128 row_shr:2 row_mask:0xf bank_mask:0xf
	v_fmac_f32_dpp v165, v57, v129 row_shr:2 row_mask:0xf bank_mask:0xf
	v_fmac_f32_dpp v166, v58, v130 row_shr:2 row_mask:0xf bank_mask:0xf
	v_fmac_f32_dpp v167, v59, v131 row_shr:2 row_mask:0xf bank_mask:0xf
	v_pk_mul_f32 v[168:169], v[160:161], s[98:99]
	v_pk_mul_f32 v[170:171], v[162:163], s[98:99]
	v_exp_f32_e32 v168, v168
	v_exp_f32_e32 v169, v169
	v_exp_f32_e32 v170, v170
	v_exp_f32_e32 v171, v171
	v_pk_add_f32 v[168:169], v[168:169], s[100:101]
	v_pk_add_f32 v[170:171], v[170:171], s[100:101]
	v_rcp_f32_e32 v168, v168
	v_rcp_f32_e32 v169, v169
	v_rcp_f32_e32 v170, v170
	v_rcp_f32_e32 v171, v171
	v_mov_b64_e32 v[174:175], v[224:225]
	v_mul_f32_e32 v160, v160, v168
	v_mul_f32_e32 v161, v161, v169
	v_mul_f32_e32 v162, v162, v170
	v_mul_f32_e32 v163, v163, v171
	v_mul_f32_e32 v160, v164, v160
	v_mul_f32_e32 v161, v165, v161
	v_mul_f32_e32 v162, v166, v162
	v_mul_f32_e32 v163, v167, v163
	v_cvt_pk_bf16_f32 v172, v160, v161
; DI float silu_fast(float x) { return x * __builtin_amdgcn_rcpf(1.f + __expf(-x)); }
; template <int CTRL> DI float dppf(float v) { return __builtin_bit_cast(float, __builtin_amdgcn_update_dpp(0, __builtin_bit_cast(int, v), CTRL, 0xf, 0xf, true)); }
; DI void Epi::fused(const f32x4 (&acc)[2][2][4][2], int pm, int pn, int wr, int wc, int fr, int fq) const {
;     ...
;             for (int m = 0; m < 4; ++m) {
;                 const f32x4 ca = acc[ai][bj][m][0], cb = acc[ai][bj][m][1];
;                 const int row = pm * 256 + ai * 128 + wr * 64 + m * 16 + fr;
;                 float o[4];
; #pragma unroll
;                 for (int e = 0; e < 4; ++e) {
;                     const float a1 = dppf<0x111>(ca[e]) + dppf<0x10F>(pa[e]), a2 = dppf<0x112>(ca[e]) + dppf<0x10E>(pa[e]);
;                     const float b1 = dppf<0x111>(cb[e]) + dppf<0x10F>(pb[e]), b2 = dppf<0x112>(cb[e]) + dppf<0x10E>(pb[e]);
;                     const float ya = fmaf(wa0[e], a2, fmaf(wa1[e], a1, fmaf(wa2[e], ca[e], ba[e])));
;                     const float yb = fmaf(wb0[e], b2, fmaf(wb1[e], b1, fmaf(wb2[e], cb[e], bb[e])));
;                     o[e] = silu_fast(ya) * yb; }
;                 if (m > 0 || fr >= 2) { u32x2 w; w.x = pk2(o[0], o[1]); w.y = pk2(o[2], o[3]); *(u32x2*)(E.d0 + (size_t)row * FFH + j0) = w; }
;                 if ((m == 0 && fr < 2) || (m == 3 && fr >= 14)) { float* hb = E.f0 + ((size_t)(row >> 6) * 4 + (m == 0 ? fr : fr - 12)) * FF2 + ncol; *(f32x4*)hb = ca; *(f32x4*)(hb + 4) = cb; }
	v_cvt_pk_bf16_f32 v173, v162, v163
	s_and_saveexec_b64 s[76:77], s[38:39]
	global_store_dwordx2 v[174:175], v[172:173], off
	s_or_b64 exec, exec, s[76:77]
	s_ashr_i32 s80, s71, 6
	s_lshl_b32 s80, s80, 2
	s_add_i32 s80, s80, 8
	v_add_u32_e32 v226, s80, v188
	v_mov_b64_e32 v[174:175], s[8:9]
	s_movk_i32 s80, 0x5800
	v_mad_i64_i32 v[174:175], s[78:79], v226, s80, v[174:175]
	v_lshl_add_u64 v[174:175], v[228:229], 2, v[174:175]
	s_and_saveexec_b64 s[76:77], s[40:41]
	global_store_dwordx4 v[174:175], v[60:63], off
	global_store_dwordx4 v[174:175], v[56:59], off offset:16
	s_or_b64 exec, exec, s[76:77]
	v_fma_f32 v208, v152, v52, v156
	v_fma_f32 v209, v153, v53, v157
	v_fma_f32 v210, v154, v54, v158
	v_fma_f32 v211, v155, v55, v159
	v_fma_f32 v212, v144, v40, v148
	v_fma_f32 v213, v145, v41, v149
	v_fma_f32 v214, v146, v42, v150
	v_fma_f32 v215, v147, v43, v151
	v_fmac_f32_dpp v208, v52, v140 row_shr:1 row_mask:0xf bank_mask:0xf
	v_fmac_f32_dpp v209, v53, v141 row_shr:1 row_mask:0xf bank_mask:0xf
	v_fmac_f32_dpp v210, v54, v142 row_shr:1 row_mask:0xf bank_mask:0xf
	v_fmac_f32_dpp v211, v55, v143 row_shr:1 row_mask:0xf bank_mask:0xf
	v_fmac_f32_dpp v212, v40, v132 row_shr:1 row_mask:0xf bank_mask:0xf
	v_fmac_f32_dpp v213, v41, v133 row_shr:1 row_mask:0xf bank_mask:0xf
	v_fmac_f32_dpp v214, v42, v134 row_shr:1 row_mask:0xf bank_mask:0xf
	v_fmac_f32_dpp v215, v43, v135 row_shr:1 row_mask:0xf bank_mask:0xf
	v_fmac_f32_dpp v208, v60, v140 row_shl:15 row_mask:0xf bank_mask:0xf
	v_fmac_f32_dpp v209, v61, v141 row_shl:15 row_mask:0xf bank_mask:0xf
	v_fmac_f32_dpp v210, v62, v142 row_shl:15 row_mask:0xf bank_mask:0xf
	v_fmac_f32_dpp v211, v63, v143 row_shl:15 row_mask:0xf bank_mask:0xf
	v_fmac_f32_dpp v212, v56, v132 row_shl:15 row_mask:0xf bank_mask:0xf
	v_fmac_f32_dpp v213, v57, v133 row_shl:15 row_mask:0xf bank_mask:0xf
	v_fmac_f32_dpp v214, v58, v134 row_shl:15 row_mask:0xf bank_mask:0xf
	v_fmac_f32_dpp v215, v59, v135 row_shl:15 row_mask:0xf bank_mask:0xf
	v_fmac_f32_dpp v208, v52, v136 row_shr:2 row_mask:0xf bank_mask:0xf
	v_fmac_f32_dpp v209, v53, v137 row_shr:2 row_mask:0xf bank_mask:0xf
	v_fmac_f32_dpp v210, v54, v138 row_shr:2 row_mask:0xf bank_mask:0xf
	v_fmac_f32_dpp v211, v55, v139 row_shr:2 row_mask:0xf bank_mask:0xf
	v_fmac_f32_dpp v212, v40, v128 row_shr:2 row_mask:0xf bank_mask:0xf
	v_fmac_f32_dpp v213, v41, v129 row_shr:2 row_mask:0xf bank_mask:0xf
	v_fmac_f32_dpp v214, v42, v130 row_shr:2 row_mask:0xf bank_mask:0xf
	v_fmac_f32_dpp v215, v43, v131 row_shr:2 row_mask:0xf bank_mask:0xf
	v_fmac_f32_dpp v208, v60, v136 row_shl:14 row_mask:0xf bank_mask:0xf
	v_fmac_f32_dpp v209, v61, v137 row_shl:14 row_mask:0xf bank_mask:0xf
	v_fmac_f32_dpp v210, v62, v138 row_shl:14 row_mask:0xf bank_mask:0xf
	v_fmac_f32_dpp v211, v63, v139 row_shl:14 row_mask:0xf bank_mask:0xf
	v_fmac_f32_dpp v212, v56, v128 row_shl:14 row_mask:0xf bank_mask:0xf
	v_fmac_f32_dpp v213, v57, v129 row_shl:14 row_mask:0xf bank_mask:0xf
	v_fmac_f32_dpp v214, v58, v130 row_shl:14 row_mask:0xf bank_mask:0xf
	v_fmac_f32_dpp v215, v59, v131 row_shl:14 row_mask:0xf bank_mask:0xf
	v_pk_mul_f32 v[216:217], v[208:209], s[98:99]
	v_pk_mul_f32 v[218:219], v[210:211], s[98:99]
	v_exp_f32_e32 v216, v216
	v_exp_f32_e32 v217, v217
	v_exp_f32_e32 v218, v218
	v_exp_f32_e32 v219, v219
	v_pk_add_f32 v[216:217], v[216:217], s[100:101]
	v_pk_add_f32 v[218:219], v[218:219], s[100:101]
	v_rcp_f32_e32 v216, v216
	v_rcp_f32_e32 v217, v217
	v_rcp_f32_e32 v218, v218
	v_rcp_f32_e32 v219, v219
	s_mov_b32 s80, 0x16000
	s_mov_b32 s81, 0
	v_lshl_add_u64 v[222:223], v[224:225], 0, s[80:81]
	v_mul_f32_e32 v208, v208, v216
	v_mul_f32_e32 v209, v209, v217
	v_mul_f32_e32 v210, v210, v218
	v_mul_f32_e32 v211, v211, v219
	v_mul_f32_e32 v208, v212, v208
	v_mul_f32_e32 v209, v213, v209
	v_mul_f32_e32 v210, v214, v210
	v_mul_f32_e32 v211, v215, v211
	v_cvt_pk_bf16_f32 v220, v208, v209
	v_cvt_pk_bf16_f32 v221, v210, v211
	global_store_dwordx2 v[222:223], v[220:221], off
	v_fma_f32 v160, v152, v36, v156
	v_fma_f32 v161, v153, v37, v157
	v_fma_f32 v162, v154, v38, v158
	v_fma_f32 v163, v155, v39, v159
	v_fma_f32 v164, v144, v16, v148
	v_fma_f32 v165, v145, v17, v149
	v_fma_f32 v166, v146, v18, v150
	v_fma_f32 v167, v147, v19, v151
	v_fmac_f32_dpp v160, v36, v140 row_shr:1 row_mask:0xf bank_mask:0xf
	v_fmac_f32_dpp v161, v37, v141 row_shr:1 row_mask:0xf bank_mask:0xf
	v_fmac_f32_dpp v162, v38, v142 row_shr:1 row_mask:0xf bank_mask:0xf
	v_fmac_f32_dpp v163, v39, v143 row_shr:1 row_mask:0xf bank_mask:0xf
	v_fmac_f32_dpp v164, v16, v132 row_shr:1 row_mask:0xf bank_mask:0xf
	v_fmac_f32_dpp v165, v17, v133 row_shr:1 row_mask:0xf bank_mask:0xf
	v_fmac_f32_dpp v166, v18, v134 row_shr:1 row_mask:0xf bank_mask:0xf
	v_fmac_f32_dpp v167, v19, v135 row_shr:1 row_mask:0xf bank_mask:0xf
	v_fmac_f32_dpp v160, v52, v140 row_shl:15 row_mask:0xf bank_mask:0xf
	v_fmac_f32_dpp v161, v53, v141 row_shl:15 row_mask:0xf bank_mask:0xf
	v_fmac_f32_dpp v162, v54, v142 row_shl:15 row_mask:0xf bank_mask:0xf
	v_fmac_f32_dpp v163, v55, v143 row_shl:15 row_mask:0xf bank_mask:0xf
	v_fmac_f32_dpp v164, v40, v132 row_shl:15 row_mask:0xf bank_mask:0xf
	v_fmac_f32_dpp v165, v41, v133 row_shl:15 row_mask:0xf bank_mask:0xf
	v_fmac_f32_dpp v166, v42, v134 row_shl:15 row_mask:0xf bank_mask:0xf
	v_fmac_f32_dpp v167, v43, v135 row_shl:15 row_mask:0xf bank_mask:0xf
	v_fmac_f32_dpp v160, v36, v136 row_shr:2 row_mask:0xf bank_mask:0xf
	v_fmac_f32_dpp v161, v37, v137 row_shr:2 row_mask:0xf bank_mask:0xf
	v_fmac_f32_dpp v162, v38, v138 row_shr:2 row_mask:0xf bank_mask:0xf
	v_fmac_f32_dpp v163, v39, v139 row_shr:2 row_mask:0xf bank_mask:0xf
; DI float silu_fast(float x) { return x * __builtin_amdgcn_rcpf(1.f + __expf(-x)); }
; template <int CTRL> DI float dppf(float v) { return __builtin_bit_cast(float, __builtin_amdgcn_update_dpp(0, __builtin_bit_cast(int, v), CTRL, 0xf, 0xf, true)); }
; DI void Epi::fused(const f32x4 (&acc)[2][2][4][2], int pm, int pn, int wr, int wc, int fr, int fq) const {
;     ...
;             for (int m = 0; m < 4; ++m) {
;                 const f32x4 ca = acc[ai][bj][m][0], cb = acc[ai][bj][m][1];
;                 const int row = pm * 256 + ai * 128 + wr * 64 + m * 16 + fr;
;                 float o[4];
; #pragma unroll
;                 for (int e = 0; e < 4; ++e) {
;                     const float a1 = dppf<0x111>(ca[e]) + dppf<0x10F>(pa[e]), a2 = dppf<0x112>(ca[e]) + dppf<0x10E>(pa[e]);
;                     const float b1 = dppf<0x111>(cb[e]) + dppf<0x10F>(pb[e]), b2 = dppf<0x112>(cb[e]) + dppf<0x10E>(pb[e]);
;                     const float ya = fmaf(wa0[e], a2, fmaf(wa1[e], a1, fmaf(wa2[e], ca[e], ba[e])));
;                     const float yb = fmaf(wb0[e], b2, fmaf(wb1[e], b1, fmaf(wb2[e], cb[e], bb[e])));
;                     o[e] = silu_fast(ya) * yb; }
;                 if (m > 0 || fr >= 2) { u32x2 w; w.x = pk2(o[0], o[1]); w.y = pk2(o[2], o[3]); *(u32x2*)(E.d0 + (size_t)row * FFH + j0) = w; }
;                 if ((m == 0 && fr < 2) || (m == 3 && fr >= 14)) { float* hb = E.f0 + ((size_t)(row >> 6) * 4 + (m == 0 ? fr : fr - 12)) * FF2 + ncol; *(f32x4*)hb = ca; *(f32x4*)(hb + 4) = cb; }
	v_fmac_f32_dpp v164, v16, v128 row_shr:2 row_mask:0xf bank_mask:0xf
	v_fmac_f32_dpp v165, v17, v129 row_shr:2 row_mask:0xf bank_mask:0xf
	v_fmac_f32_dpp v166, v18, v130 row_shr:2 row_mask:0xf bank_mask:0xf
	v_fmac_f32_dpp v167, v19, v131 row_shr:2 row_mask:0xf bank_mask:0xf
	v_fmac_f32_dpp v160, v52, v136 row_shl:14 row_mask:0xf bank_mask:0xf
	v_fmac_f32_dpp v161, v53, v137 row_shl:14 row_mask:0xf bank_mask:0xf
	v_fmac_f32_dpp v162, v54, v138 row_shl:14 row_mask:0xf bank_mask:0xf
	v_fmac_f32_dpp v163, v55, v139 row_shl:14 row_mask:0xf bank_mask:0xf
	v_fmac_f32_dpp v164, v40, v128 row_shl:14 row_mask:0xf bank_mask:0xf
	v_fmac_f32_dpp v165, v41, v129 row_shl:14 row_mask:0xf bank_mask:0xf
	v_fmac_f32_dpp v166, v42, v130 row_shl:14 row_mask:0xf bank_mask:0xf
	v_fmac_f32_dpp v167, v43, v131 row_shl:14 row_mask:0xf bank_mask:0xf
	v_pk_mul_f32 v[168:169], v[160:161], s[98:99]
	v_pk_mul_f32 v[170:171], v[162:163], s[98:99]
	v_exp_f32_e32 v168, v168
	v_exp_f32_e32 v169, v169
	v_exp_f32_e32 v170, v170
	v_exp_f32_e32 v171, v171
	v_pk_add_f32 v[168:169], v[168:169], s[100:101]
	v_pk_add_f32 v[170:171], v[170:171], s[100:101]
	v_rcp_f32_e32 v168, v168
	v_rcp_f32_e32 v169, v169
	v_rcp_f32_e32 v170, v170
	v_rcp_f32_e32 v171, v171
	s_mov_b32 s80, 0x2c000
	s_mov_b32 s81, 0
	v_lshl_add_u64 v[174:175], v[224:225], 0, s[80:81]
	v_mul_f32_e32 v160, v160, v168
	v_mul_f32_e32 v161, v161, v169
	v_mul_f32_e32 v162, v162, v170
	v_mul_f32_e32 v163, v163, v171
	v_mul_f32_e32 v160, v164, v160
	v_mul_f32_e32 v161, v165, v161
	v_mul_f32_e32 v162, v166, v162
	v_mul_f32_e32 v163, v167, v163
	v_cvt_pk_bf16_f32 v172, v160, v161
	v_cvt_pk_bf16_f32 v173, v162, v163
	global_store_dwordx2 v[174:175], v[172:173], off
	v_fma_f32 v208, v152, v12, v156
	v_fma_f32 v209, v153, v13, v157
	v_fma_f32 v210, v154, v14, v158
	v_fma_f32 v211, v155, v15, v159
	v_fma_f32 v212, v144, v0, v148
	v_fma_f32 v213, v145, v1, v149
	v_fma_f32 v214, v146, v2, v150
	v_fma_f32 v215, v147, v3, v151
	v_fmac_f32_dpp v208, v12, v140 row_shr:1 row_mask:0xf bank_mask:0xf
	v_fmac_f32_dpp v209, v13, v141 row_shr:1 row_mask:0xf bank_mask:0xf
	v_fmac_f32_dpp v210, v14, v142 row_shr:1 row_mask:0xf bank_mask:0xf
	v_fmac_f32_dpp v211, v15, v143 row_shr:1 row_mask:0xf bank_mask:0xf
	v_fmac_f32_dpp v212, v0, v132 row_shr:1 row_mask:0xf bank_mask:0xf
	v_fmac_f32_dpp v213, v1, v133 row_shr:1 row_mask:0xf bank_mask:0xf
	v_fmac_f32_dpp v214, v2, v134 row_shr:1 row_mask:0xf bank_mask:0xf
	v_fmac_f32_dpp v215, v3, v135 row_shr:1 row_mask:0xf bank_mask:0xf
	v_fmac_f32_dpp v208, v36, v140 row_shl:15 row_mask:0xf bank_mask:0xf
	v_fmac_f32_dpp v209, v37, v141 row_shl:15 row_mask:0xf bank_mask:0xf
	v_fmac_f32_dpp v210, v38, v142 row_shl:15 row_mask:0xf bank_mask:0xf
	v_fmac_f32_dpp v211, v39, v143 row_shl:15 row_mask:0xf bank_mask:0xf
	v_fmac_f32_dpp v212, v16, v132 row_shl:15 row_mask:0xf bank_mask:0xf
	v_fmac_f32_dpp v213, v17, v133 row_shl:15 row_mask:0xf bank_mask:0xf
	v_fmac_f32_dpp v214, v18, v134 row_shl:15 row_mask:0xf bank_mask:0xf
	v_fmac_f32_dpp v215, v19, v135 row_shl:15 row_mask:0xf bank_mask:0xf
	v_fmac_f32_dpp v208, v12, v136 row_shr:2 row_mask:0xf bank_mask:0xf
	v_fmac_f32_dpp v209, v13, v137 row_shr:2 row_mask:0xf bank_mask:0xf
	v_fmac_f32_dpp v210, v14, v138 row_shr:2 row_mask:0xf bank_mask:0xf
	v_fmac_f32_dpp v211, v15, v139 row_shr:2 row_mask:0xf bank_mask:0xf
	v_fmac_f32_dpp v212, v0, v128 row_shr:2 row_mask:0xf bank_mask:0xf
	v_fmac_f32_dpp v213, v1, v129 row_shr:2 row_mask:0xf bank_mask:0xf
	v_fmac_f32_dpp v214, v2, v130 row_shr:2 row_mask:0xf bank_mask:0xf
	v_fmac_f32_dpp v215, v3, v131 row_shr:2 row_mask:0xf bank_mask:0xf
	v_fmac_f32_dpp v208, v36, v136 row_shl:14 row_mask:0xf bank_mask:0xf
	v_fmac_f32_dpp v209, v37, v137 row_shl:14 row_mask:0xf bank_mask:0xf
	v_fmac_f32_dpp v210, v38, v138 row_shl:14 row_mask:0xf bank_mask:0xf
	v_fmac_f32_dpp v211, v39, v139 row_shl:14 row_mask:0xf bank_mask:0xf
	v_fmac_f32_dpp v212, v16, v128 row_shl:14 row_mask:0xf bank_mask:0xf
	v_fmac_f32_dpp v213, v17, v129 row_shl:14 row_mask:0xf bank_mask:0xf
	v_fmac_f32_dpp v214, v18, v130 row_shl:14 row_mask:0xf bank_mask:0xf
	v_fmac_f32_dpp v215, v19, v131 row_shl:14 row_mask:0xf bank_mask:0xf
	v_pk_mul_f32 v[216:217], v[208:209], s[98:99]
	v_pk_mul_f32 v[218:219], v[210:211], s[98:99]
	v_exp_f32_e32 v216, v216
	v_exp_f32_e32 v217, v217
	v_exp_f32_e32 v218, v218
	v_exp_f32_e32 v219, v219
	v_pk_add_f32 v[216:217], v[216:217], s[100:101]
	v_pk_add_f32 v[218:219], v[218:219], s[100:101]
	v_rcp_f32_e32 v216, v216
	v_rcp_f32_e32 v217, v217
	v_rcp_f32_e32 v218, v218
	v_rcp_f32_e32 v219, v219
	s_mov_b32 s80, 0x42000
	s_mov_b32 s81, 0
	v_lshl_add_u64 v[222:223], v[224:225], 0, s[80:81]
	v_mul_f32_e32 v208, v208, v216
	v_mul_f32_e32 v209, v209, v217
	v_mul_f32_e32 v210, v210, v218
	v_mul_f32_e32 v211, v211, v219
	v_mul_f32_e32 v208, v212, v208
	v_mul_f32_e32 v209, v213, v209
	v_mul_f32_e32 v210, v214, v210
	v_mul_f32_e32 v211, v215, v211
	v_cvt_pk_bf16_f32 v220, v208, v209
	v_cvt_pk_bf16_f32 v221, v210, v211
	global_store_dwordx2 v[222:223], v[220:221], off
	s_ashr_i32 s80, s71, 6
	s_lshl_b32 s80, s80, 2
	s_add_i32 s80, s80, 8
	v_add_u32_e32 v226, s80, v190
	v_mov_b64_e32 v[222:223], s[8:9]
	s_movk_i32 s80, 0x5800
	v_mad_i64_i32 v[222:223], s[78:79], v226, s80, v[222:223]
	v_lshl_add_u64 v[222:223], v[228:229], 2, v[222:223]
	s_and_saveexec_b64 s[76:77], s[42:43]
	global_store_dwordx4 v[222:223], v[12:15], off
	global_store_dwordx4 v[222:223], v[0:3], off offset:16
	s_or_b64 exec, exec, s[76:77]
	v_mov_b32_e32 v228, v199
	v_mov_b64_e32 v[224:225], s[12:13]
	s_movk_i32 s80, 0x1600
	v_mad_i64_i32 v[224:225], s[78:79], v228, s80, v[224:225]
	v_add_u32_e32 v228, 128, v240
	v_mov_b32_e32 v229, 0
	v_lshl_add_u64 v[224:225], v[228:229], 0, v[224:225]
	s_waitcnt vmcnt(8)
; DI float silu_fast(float x) { return x * __builtin_amdgcn_rcpf(1.f + __expf(-x)); }
; template <int CTRL> DI float dppf(float v) { return __builtin_bit_cast(float, __builtin_amdgcn_update_dpp(0, __builtin_bit_cast(int, v), CTRL, 0xf, 0xf, true)); }
; DI void Epi::fused(const f32x4 (&acc)[2][2][4][2], int pm, int pn, int wr, int wc, int fr, int fq) const {
;     ...
;             for (int m = 0; m < 4; ++m) {
;                 const f32x4 ca = acc[ai][bj][m][0], cb = acc[ai][bj][m][1];
;                 const int row = pm * 256 + ai * 128 + wr * 64 + m * 16 + fr;
;                 float o[4];
; #pragma unroll
;                 for (int e = 0; e < 4; ++e) {
;                     const float a1 = dppf<0x111>(ca[e]) + dppf<0x10F>(pa[e]), a2 = dppf<0x112>(ca[e]) + dppf<0x10E>(pa[e]);
;                     const float b1 = dppf<0x111>(cb[e]) + dppf<0x10F>(pb[e]), b2 = dppf<0x112>(cb[e]) + dppf<0x10E>(pb[e]);
;                     const float ya = fmaf(wa0[e], a2, fmaf(wa1[e], a1, fmaf(wa2[e], ca[e], ba[e])));
;                     const float yb = fmaf(wb0[e], b2, fmaf(wb1[e], b1, fmaf(wb2[e], cb[e], bb[e])));
;                     o[e] = silu_fast(ya) * yb; }
;                 if (m > 0 || fr >= 2) { u32x2 w; w.x = pk2(o[0], o[1]); w.y = pk2(o[2], o[3]); *(u32x2*)(E.d0 + (size_t)row * FFH + j0) = w; }
;                 if ((m == 0 && fr < 2) || (m == 3 && fr >= 14)) { float* hb = E.f0 + ((size_t)(row >> 6) * 4 + (m == 0 ? fr : fr - 12)) * FF2 + ncol; *(f32x4*)hb = ca; *(f32x4*)(hb + 4) = cb; }
	v_fma_f32 v160, v100, v112, v124
	v_fma_f32 v161, v101, v113, v125
	v_fma_f32 v162, v102, v114, v126
	v_fma_f32 v163, v103, v115, v127
	v_fma_f32 v164, v120, v108, v72
	v_fma_f32 v165, v121, v109, v73
	v_fma_f32 v166, v122, v110, v74
	v_fma_f32 v167, v123, v111, v75
	v_fmac_f32_dpp v160, v112, v88 row_shr:1 row_mask:0xf bank_mask:0xf
	v_fmac_f32_dpp v161, v113, v89 row_shr:1 row_mask:0xf bank_mask:0xf
	v_fmac_f32_dpp v162, v114, v90 row_shr:1 row_mask:0xf bank_mask:0xf
	v_fmac_f32_dpp v163, v115, v91 row_shr:1 row_mask:0xf bank_mask:0xf
	v_fmac_f32_dpp v164, v108, v116 row_shr:1 row_mask:0xf bank_mask:0xf
	v_fmac_f32_dpp v165, v109, v117 row_shr:1 row_mask:0xf bank_mask:0xf
	v_fmac_f32_dpp v166, v110, v118 row_shr:1 row_mask:0xf bank_mask:0xf
	v_fmac_f32_dpp v167, v111, v119 row_shr:1 row_mask:0xf bank_mask:0xf
	v_fmac_f32_dpp v160, v112, v84 row_shr:2 row_mask:0xf bank_mask:0xf
	v_fmac_f32_dpp v161, v113, v85 row_shr:2 row_mask:0xf bank_mask:0xf
	v_fmac_f32_dpp v162, v114, v86 row_shr:2 row_mask:0xf bank_mask:0xf
	v_fmac_f32_dpp v163, v115, v87 row_shr:2 row_mask:0xf bank_mask:0xf
	v_fmac_f32_dpp v164, v108, v104 row_shr:2 row_mask:0xf bank_mask:0xf
	v_fmac_f32_dpp v165, v109, v105 row_shr:2 row_mask:0xf bank_mask:0xf
	v_fmac_f32_dpp v166, v110, v106 row_shr:2 row_mask:0xf bank_mask:0xf
	v_fmac_f32_dpp v167, v111, v107 row_shr:2 row_mask:0xf bank_mask:0xf
	v_pk_mul_f32 v[168:169], v[160:161], s[98:99]
	v_pk_mul_f32 v[170:171], v[162:163], s[98:99]
	v_exp_f32_e32 v168, v168
	v_exp_f32_e32 v169, v169
	v_exp_f32_e32 v170, v170
	v_exp_f32_e32 v171, v171
	v_pk_add_f32 v[168:169], v[168:169], s[100:101]
	v_pk_add_f32 v[170:171], v[170:171], s[100:101]
	v_rcp_f32_e32 v168, v168
	v_rcp_f32_e32 v169, v169
	v_rcp_f32_e32 v170, v170
	v_rcp_f32_e32 v171, v171
	v_mov_b64_e32 v[174:175], v[224:225]
	v_mul_f32_e32 v160, v160, v168
	v_mul_f32_e32 v161, v161, v169
	v_mul_f32_e32 v162, v162, v170
	v_mul_f32_e32 v163, v163, v171
	v_mul_f32_e32 v160, v164, v160
	v_mul_f32_e32 v161, v165, v161
	v_mul_f32_e32 v162, v166, v162
	v_mul_f32_e32 v163, v167, v163
	v_cvt_pk_bf16_f32 v172, v160, v161
	v_cvt_pk_bf16_f32 v173, v162, v163
	s_and_saveexec_b64 s[76:77], s[38:39]
	global_store_dwordx2 v[174:175], v[172:173], off
	s_or_b64 exec, exec, s[76:77]
	s_ashr_i32 s80, s71, 6
	s_lshl_b32 s80, s80, 2
	v_add_u32_e32 v226, s80, v188
	v_mov_b64_e32 v[174:175], s[8:9]
	s_movk_i32 s80, 0x5800
	v_mad_i64_i32 v[174:175], s[78:79], v226, s80, v[174:175]
	v_lshl_add_u64 v[174:175], v[228:229], 2, v[174:175]
	s_and_saveexec_b64 s[76:77], s[40:41]
	global_store_dwordx4 v[174:175], v[112:115], off
	global_store_dwordx4 v[174:175], v[108:111], off offset:16
	s_or_b64 exec, exec, s[76:77]
	v_fma_f32 v208, v100, v96, v124
	v_fma_f32 v209, v101, v97, v125
	v_fma_f32 v210, v102, v98, v126
	v_fma_f32 v211, v103, v99, v127
	v_fma_f32 v212, v120, v92, v72
	v_fma_f32 v213, v121, v93, v73
	v_fma_f32 v214, v122, v94, v74
	v_fma_f32 v215, v123, v95, v75
	v_fmac_f32_dpp v208, v96, v88 row_shr:1 row_mask:0xf bank_mask:0xf
	v_fmac_f32_dpp v209, v97, v89 row_shr:1 row_mask:0xf bank_mask:0xf
	v_fmac_f32_dpp v210, v98, v90 row_shr:1 row_mask:0xf bank_mask:0xf
	v_fmac_f32_dpp v211, v99, v91 row_shr:1 row_mask:0xf bank_mask:0xf
	v_fmac_f32_dpp v212, v92, v116 row_shr:1 row_mask:0xf bank_mask:0xf
	v_fmac_f32_dpp v213, v93, v117 row_shr:1 row_mask:0xf bank_mask:0xf
	v_fmac_f32_dpp v214, v94, v118 row_shr:1 row_mask:0xf bank_mask:0xf
	v_fmac_f32_dpp v215, v95, v119 row_shr:1 row_mask:0xf bank_mask:0xf
	v_fmac_f32_dpp v208, v112, v88 row_shl:15 row_mask:0xf bank_mask:0xf
	v_fmac_f32_dpp v209, v113, v89 row_shl:15 row_mask:0xf bank_mask:0xf
	v_fmac_f32_dpp v210, v114, v90 row_shl:15 row_mask:0xf bank_mask:0xf
	v_fmac_f32_dpp v211, v115, v91 row_shl:15 row_mask:0xf bank_mask:0xf
	v_fmac_f32_dpp v212, v108, v116 row_shl:15 row_mask:0xf bank_mask:0xf
	v_fmac_f32_dpp v213, v109, v117 row_shl:15 row_mask:0xf bank_mask:0xf
	v_fmac_f32_dpp v214, v110, v118 row_shl:15 row_mask:0xf bank_mask:0xf
	v_fmac_f32_dpp v215, v111, v119 row_shl:15 row_mask:0xf bank_mask:0xf
	v_fmac_f32_dpp v208, v96, v84 row_shr:2 row_mask:0xf bank_mask:0xf
	v_fmac_f32_dpp v209, v97, v85 row_shr:2 row_mask:0xf bank_mask:0xf
	v_fmac_f32_dpp v210, v98, v86 row_shr:2 row_mask:0xf bank_mask:0xf
	v_fmac_f32_dpp v211, v99, v87 row_shr:2 row_mask:0xf bank_mask:0xf
	v_fmac_f32_dpp v212, v92, v104 row_shr:2 row_mask:0xf bank_mask:0xf
	v_fmac_f32_dpp v213, v93, v105 row_shr:2 row_mask:0xf bank_mask:0xf
	v_fmac_f32_dpp v214, v94, v106 row_shr:2 row_mask:0xf bank_mask:0xf
	v_fmac_f32_dpp v215, v95, v107 row_shr:2 row_mask:0xf bank_mask:0xf
	v_fmac_f32_dpp v208, v112, v84 row_shl:14 row_mask:0xf bank_mask:0xf
	v_fmac_f32_dpp v209, v113, v85 row_shl:14 row_mask:0xf bank_mask:0xf
	v_fmac_f32_dpp v210, v114, v86 row_shl:14 row_mask:0xf bank_mask:0xf
	v_fmac_f32_dpp v211, v115, v87 row_shl:14 row_mask:0xf bank_mask:0xf
	v_fmac_f32_dpp v212, v108, v104 row_shl:14 row_mask:0xf bank_mask:0xf
	v_fmac_f32_dpp v213, v109, v105 row_shl:14 row_mask:0xf bank_mask:0xf
	v_fmac_f32_dpp v214, v110, v106 row_shl:14 row_mask:0xf bank_mask:0xf
	v_fmac_f32_dpp v215, v111, v107 row_shl:14 row_mask:0xf bank_mask:0xf
	v_pk_mul_f32 v[216:217], v[208:209], s[98:99]
	v_pk_mul_f32 v[218:219], v[210:211], s[98:99]
	v_exp_f32_e32 v216, v216
	v_exp_f32_e32 v217, v217
	v_exp_f32_e32 v218, v218
	v_exp_f32_e32 v219, v219
	v_pk_add_f32 v[216:217], v[216:217], s[100:101]
	v_pk_add_f32 v[218:219], v[218:219], s[100:101]
	v_rcp_f32_e32 v216, v216
	v_rcp_f32_e32 v217, v217
	v_rcp_f32_e32 v218, v218
	v_rcp_f32_e32 v219, v219
	s_mov_b32 s80, 0x16000
	s_mov_b32 s81, 0
; DI float silu_fast(float x) { return x * __builtin_amdgcn_rcpf(1.f + __expf(-x)); }
; template <int CTRL> DI float dppf(float v) { return __builtin_bit_cast(float, __builtin_amdgcn_update_dpp(0, __builtin_bit_cast(int, v), CTRL, 0xf, 0xf, true)); }
; DI void Epi::fused(const f32x4 (&acc)[2][2][4][2], int pm, int pn, int wr, int wc, int fr, int fq) const {
;     ...
;             for (int m = 0; m < 4; ++m) {
;                 const f32x4 ca = acc[ai][bj][m][0], cb = acc[ai][bj][m][1];
;                 const int row = pm * 256 + ai * 128 + wr * 64 + m * 16 + fr;
;                 float o[4];
; #pragma unroll
;                 for (int e = 0; e < 4; ++e) {
;                     const float a1 = dppf<0x111>(ca[e]) + dppf<0x10F>(pa[e]), a2 = dppf<0x112>(ca[e]) + dppf<0x10E>(pa[e]);
;                     const float b1 = dppf<0x111>(cb[e]) + dppf<0x10F>(pb[e]), b2 = dppf<0x112>(cb[e]) + dppf<0x10E>(pb[e]);
;                     const float ya = fmaf(wa0[e], a2, fmaf(wa1[e], a1, fmaf(wa2[e], ca[e], ba[e])));
;                     const float yb = fmaf(wb0[e], b2, fmaf(wb1[e], b1, fmaf(wb2[e], cb[e], bb[e])));
;                     o[e] = silu_fast(ya) * yb; }
;                 if (m > 0 || fr >= 2) { u32x2 w; w.x = pk2(o[0], o[1]); w.y = pk2(o[2], o[3]); *(u32x2*)(E.d0 + (size_t)row * FFH + j0) = w; }
	v_lshl_add_u64 v[222:223], v[224:225], 0, s[80:81]
	v_mul_f32_e32 v208, v208, v216
	v_mul_f32_e32 v209, v209, v217
	v_mul_f32_e32 v210, v210, v218
	v_mul_f32_e32 v211, v211, v219
	v_mul_f32_e32 v208, v212, v208
	v_mul_f32_e32 v209, v213, v209
	v_mul_f32_e32 v210, v214, v210
	v_mul_f32_e32 v211, v215, v211
	v_cvt_pk_bf16_f32 v220, v208, v209
	v_cvt_pk_bf16_f32 v221, v210, v211
	global_store_dwordx2 v[222:223], v[220:221], off
	v_fma_f32 v160, v100, v80, v124
	v_fma_f32 v161, v101, v81, v125
	v_fma_f32 v162, v102, v82, v126
	v_fma_f32 v163, v103, v83, v127
	v_fma_f32 v164, v120, v76, v72
	v_fma_f32 v165, v121, v77, v73
	v_fma_f32 v166, v122, v78, v74
	v_fma_f32 v167, v123, v79, v75
	v_fmac_f32_dpp v160, v80, v88 row_shr:1 row_mask:0xf bank_mask:0xf
	v_fmac_f32_dpp v161, v81, v89 row_shr:1 row_mask:0xf bank_mask:0xf
	v_fmac_f32_dpp v162, v82, v90 row_shr:1 row_mask:0xf bank_mask:0xf
	v_fmac_f32_dpp v163, v83, v91 row_shr:1 row_mask:0xf bank_mask:0xf
	v_fmac_f32_dpp v164, v76, v116 row_shr:1 row_mask:0xf bank_mask:0xf
	v_fmac_f32_dpp v165, v77, v117 row_shr:1 row_mask:0xf bank_mask:0xf
	v_fmac_f32_dpp v166, v78, v118 row_shr:1 row_mask:0xf bank_mask:0xf
	v_fmac_f32_dpp v167, v79, v119 row_shr:1 row_mask:0xf bank_mask:0xf
	v_fmac_f32_dpp v160, v96, v88 row_shl:15 row_mask:0xf bank_mask:0xf
	v_fmac_f32_dpp v161, v97, v89 row_shl:15 row_mask:0xf bank_mask:0xf
	v_fmac_f32_dpp v162, v98, v90 row_shl:15 row_mask:0xf bank_mask:0xf
	v_fmac_f32_dpp v163, v99, v91 row_shl:15 row_mask:0xf bank_mask:0xf
	v_fmac_f32_dpp v164, v92, v116 row_shl:15 row_mask:0xf bank_mask:0xf
	v_fmac_f32_dpp v165, v93, v117 row_shl:15 row_mask:0xf bank_mask:0xf
	v_fmac_f32_dpp v166, v94, v118 row_shl:15 row_mask:0xf bank_mask:0xf
	v_fmac_f32_dpp v167, v95, v119 row_shl:15 row_mask:0xf bank_mask:0xf
	v_fmac_f32_dpp v160, v80, v84 row_shr:2 row_mask:0xf bank_mask:0xf
	v_fmac_f32_dpp v161, v81, v85 row_shr:2 row_mask:0xf bank_mask:0xf
	v_fmac_f32_dpp v162, v82, v86 row_shr:2 row_mask:0xf bank_mask:0xf
	v_fmac_f32_dpp v163, v83, v87 row_shr:2 row_mask:0xf bank_mask:0xf
	v_fmac_f32_dpp v164, v76, v104 row_shr:2 row_mask:0xf bank_mask:0xf
	v_fmac_f32_dpp v165, v77, v105 row_shr:2 row_mask:0xf bank_mask:0xf
	v_fmac_f32_dpp v166, v78, v106 row_shr:2 row_mask:0xf bank_mask:0xf
	v_fmac_f32_dpp v167, v79, v107 row_shr:2 row_mask:0xf bank_mask:0xf
	v_fmac_f32_dpp v160, v96, v84 row_shl:14 row_mask:0xf bank_mask:0xf
	v_fmac_f32_dpp v161, v97, v85 row_shl:14 row_mask:0xf bank_mask:0xf
	v_fmac_f32_dpp v162, v98, v86 row_shl:14 row_mask:0xf bank_mask:0xf
	v_fmac_f32_dpp v163, v99, v87 row_shl:14 row_mask:0xf bank_mask:0xf
	v_fmac_f32_dpp v164, v92, v104 row_shl:14 row_mask:0xf bank_mask:0xf
	v_fmac_f32_dpp v165, v93, v105 row_shl:14 row_mask:0xf bank_mask:0xf
	v_fmac_f32_dpp v166, v94, v106 row_shl:14 row_mask:0xf bank_mask:0xf
	v_fmac_f32_dpp v167, v95, v107 row_shl:14 row_mask:0xf bank_mask:0xf
	v_pk_mul_f32 v[168:169], v[160:161], s[98:99]
	v_pk_mul_f32 v[170:171], v[162:163], s[98:99]
	v_exp_f32_e32 v168, v168
	v_exp_f32_e32 v169, v169
	v_exp_f32_e32 v170, v170
	v_exp_f32_e32 v171, v171
	v_pk_add_f32 v[168:169], v[168:169], s[100:101]
	v_pk_add_f32 v[170:171], v[170:171], s[100:101]
	v_rcp_f32_e32 v168, v168
	v_rcp_f32_e32 v169, v169
	v_rcp_f32_e32 v170, v170
	v_rcp_f32_e32 v171, v171
	s_mov_b32 s80, 0x2c000
	s_mov_b32 s81, 0
	v_lshl_add_u64 v[174:175], v[224:225], 0, s[80:81]
	v_mul_f32_e32 v160, v160, v168
	v_mul_f32_e32 v161, v161, v169
	v_mul_f32_e32 v162, v162, v170
	v_mul_f32_e32 v163, v163, v171
	v_mul_f32_e32 v160, v164, v160
	v_mul_f32_e32 v161, v165, v161
	v_mul_f32_e32 v162, v166, v162
	v_mul_f32_e32 v163, v167, v163
	v_cvt_pk_bf16_f32 v172, v160, v161
	v_cvt_pk_bf16_f32 v173, v162, v163
	global_store_dwordx2 v[174:175], v[172:173], off
	v_fma_f32 v208, v100, v68, v124
	v_fma_f32 v209, v101, v69, v125
	v_fma_f32 v210, v102, v70, v126
	v_fma_f32 v211, v103, v71, v127
	v_fma_f32 v212, v120, v64, v72
	v_fma_f32 v213, v121, v65, v73
	v_fma_f32 v214, v122, v66, v74
	v_fma_f32 v215, v123, v67, v75
	v_fmac_f32_dpp v208, v68, v88 row_shr:1 row_mask:0xf bank_mask:0xf
	v_fmac_f32_dpp v209, v69, v89 row_shr:1 row_mask:0xf bank_mask:0xf
	v_fmac_f32_dpp v210, v70, v90 row_shr:1 row_mask:0xf bank_mask:0xf
	v_fmac_f32_dpp v211, v71, v91 row_shr:1 row_mask:0xf bank_mask:0xf
	v_fmac_f32_dpp v212, v64, v116 row_shr:1 row_mask:0xf bank_mask:0xf
	v_fmac_f32_dpp v213, v65, v117 row_shr:1 row_mask:0xf bank_mask:0xf
	v_fmac_f32_dpp v214, v66, v118 row_shr:1 row_mask:0xf bank_mask:0xf
	v_fmac_f32_dpp v215, v67, v119 row_shr:1 row_mask:0xf bank_mask:0xf
	v_fmac_f32_dpp v208, v80, v88 row_shl:15 row_mask:0xf bank_mask:0xf
	v_fmac_f32_dpp v209, v81, v89 row_shl:15 row_mask:0xf bank_mask:0xf
	v_fmac_f32_dpp v210, v82, v90 row_shl:15 row_mask:0xf bank_mask:0xf
	v_fmac_f32_dpp v211, v83, v91 row_shl:15 row_mask:0xf bank_mask:0xf
	v_fmac_f32_dpp v212, v76, v116 row_shl:15 row_mask:0xf bank_mask:0xf
	v_fmac_f32_dpp v213, v77, v117 row_shl:15 row_mask:0xf bank_mask:0xf
	v_fmac_f32_dpp v214, v78, v118 row_shl:15 row_mask:0xf bank_mask:0xf
	v_fmac_f32_dpp v215, v79, v119 row_shl:15 row_mask:0xf bank_mask:0xf
	v_fmac_f32_dpp v208, v68, v84 row_shr:2 row_mask:0xf bank_mask:0xf
	v_fmac_f32_dpp v209, v69, v85 row_shr:2 row_mask:0xf bank_mask:0xf
	v_fmac_f32_dpp v210, v70, v86 row_shr:2 row_mask:0xf bank_mask:0xf
	v_fmac_f32_dpp v211, v71, v87 row_shr:2 row_mask:0xf bank_mask:0xf
	v_fmac_f32_dpp v212, v64, v104 row_shr:2 row_mask:0xf bank_mask:0xf
	v_fmac_f32_dpp v213, v65, v105 row_shr:2 row_mask:0xf bank_mask:0xf
	v_fmac_f32_dpp v214, v66, v106 row_shr:2 row_mask:0xf bank_mask:0xf
; DI float silu_fast(float x) { return x * __builtin_amdgcn_rcpf(1.f + __expf(-x)); }
; template <int CTRL> DI float dppf(float v) { return __builtin_bit_cast(float, __builtin_amdgcn_update_dpp(0, __builtin_bit_cast(int, v), CTRL, 0xf, 0xf, true)); }
; DI void Epi::fused(const f32x4 (&acc)[2][2][4][2], int pm, int pn, int wr, int wc, int fr, int fq) const {
;     ...
;             for (int m = 0; m < 4; ++m) {
;                 const f32x4 ca = acc[ai][bj][m][0], cb = acc[ai][bj][m][1];
;                 const int row = pm * 256 + ai * 128 + wr * 64 + m * 16 + fr;
;                 float o[4];
; #pragma unroll
;                 for (int e = 0; e < 4; ++e) {
;                     const float a1 = dppf<0x111>(ca[e]) + dppf<0x10F>(pa[e]), a2 = dppf<0x112>(ca[e]) + dppf<0x10E>(pa[e]);
;                     const float b1 = dppf<0x111>(cb[e]) + dppf<0x10F>(pb[e]), b2 = dppf<0x112>(cb[e]) + dppf<0x10E>(pb[e]);
;                     const float ya = fmaf(wa0[e], a2, fmaf(wa1[e], a1, fmaf(wa2[e], ca[e], ba[e])));
;                     const float yb = fmaf(wb0[e], b2, fmaf(wb1[e], b1, fmaf(wb2[e], cb[e], bb[e])));
;                     o[e] = silu_fast(ya) * yb; }
;                 if (m > 0 || fr >= 2) { u32x2 w; w.x = pk2(o[0], o[1]); w.y = pk2(o[2], o[3]); *(u32x2*)(E.d0 + (size_t)row * FFH + j0) = w; }
;                 if ((m == 0 && fr < 2) || (m == 3 && fr >= 14)) { float* hb = E.f0 + ((size_t)(row >> 6) * 4 + (m == 0 ? fr : fr - 12)) * FF2 + ncol; *(f32x4*)hb = ca; *(f32x4*)(hb + 4) = cb; }
	v_fmac_f32_dpp v215, v67, v107 row_shr:2 row_mask:0xf bank_mask:0xf
	v_fmac_f32_dpp v208, v80, v84 row_shl:14 row_mask:0xf bank_mask:0xf
	v_fmac_f32_dpp v209, v81, v85 row_shl:14 row_mask:0xf bank_mask:0xf
	v_fmac_f32_dpp v210, v82, v86 row_shl:14 row_mask:0xf bank_mask:0xf
	v_fmac_f32_dpp v211, v83, v87 row_shl:14 row_mask:0xf bank_mask:0xf
	v_fmac_f32_dpp v212, v76, v104 row_shl:14 row_mask:0xf bank_mask:0xf
	v_fmac_f32_dpp v213, v77, v105 row_shl:14 row_mask:0xf bank_mask:0xf
	v_fmac_f32_dpp v214, v78, v106 row_shl:14 row_mask:0xf bank_mask:0xf
	v_fmac_f32_dpp v215, v79, v107 row_shl:14 row_mask:0xf bank_mask:0xf
	v_pk_mul_f32 v[216:217], v[208:209], s[98:99]
	v_pk_mul_f32 v[218:219], v[210:211], s[98:99]
	v_exp_f32_e32 v216, v216
	v_exp_f32_e32 v217, v217
	v_exp_f32_e32 v218, v218
	v_exp_f32_e32 v219, v219
	v_pk_add_f32 v[216:217], v[216:217], s[100:101]
	v_pk_add_f32 v[218:219], v[218:219], s[100:101]
	v_rcp_f32_e32 v216, v216
	v_rcp_f32_e32 v217, v217
	v_rcp_f32_e32 v218, v218
	v_rcp_f32_e32 v219, v219
	s_mov_b32 s80, 0x42000
	s_mov_b32 s81, 0
	v_lshl_add_u64 v[222:223], v[224:225], 0, s[80:81]
	v_mul_f32_e32 v208, v208, v216
	v_mul_f32_e32 v209, v209, v217
	v_mul_f32_e32 v210, v210, v218
	v_mul_f32_e32 v211, v211, v219
	v_mul_f32_e32 v208, v212, v208
	v_mul_f32_e32 v209, v213, v209
	v_mul_f32_e32 v210, v214, v210
	v_mul_f32_e32 v211, v215, v211
	v_cvt_pk_bf16_f32 v220, v208, v209
	v_cvt_pk_bf16_f32 v221, v210, v211
	global_store_dwordx2 v[222:223], v[220:221], off
	s_ashr_i32 s80, s71, 6
	s_lshl_b32 s80, s80, 2
	v_add_u32_e32 v226, s80, v190
	v_mov_b64_e32 v[222:223], s[8:9]
	s_movk_i32 s80, 0x5800
	v_mad_i64_i32 v[222:223], s[78:79], v226, s80, v[222:223]
	v_lshl_add_u64 v[222:223], v[228:229], 2, v[222:223]
	s_and_saveexec_b64 s[76:77], s[42:43]
	global_store_dwordx4 v[222:223], v[68:71], off
	global_store_dwordx4 v[222:223], v[64:67], off offset:16
	s_or_b64 exec, exec, s[76:77]
	v_add_u32_e32 v228, 128, v199
	v_mov_b64_e32 v[224:225], s[12:13]
	s_movk_i32 s80, 0x1600
	v_mad_i64_i32 v[224:225], s[78:79], v228, s80, v[224:225]
	v_add_u32_e32 v228, 128, v240
	v_mov_b32_e32 v229, 0
	v_lshl_add_u64 v[224:225], v[228:229], 0, v[224:225]
	v_fma_f32 v160, v100, v48, v124
	v_fma_f32 v161, v101, v49, v125
	v_fma_f32 v162, v102, v50, v126
	v_fma_f32 v163, v103, v51, v127
	v_fma_f32 v164, v120, v44, v72
	v_fma_f32 v165, v121, v45, v73
	v_fma_f32 v166, v122, v46, v74
	v_fma_f32 v167, v123, v47, v75
	v_fmac_f32_dpp v160, v48, v88 row_shr:1 row_mask:0xf bank_mask:0xf
	v_fmac_f32_dpp v161, v49, v89 row_shr:1 row_mask:0xf bank_mask:0xf
	v_fmac_f32_dpp v162, v50, v90 row_shr:1 row_mask:0xf bank_mask:0xf
	v_fmac_f32_dpp v163, v51, v91 row_shr:1 row_mask:0xf bank_mask:0xf
	v_fmac_f32_dpp v164, v44, v116 row_shr:1 row_mask:0xf bank_mask:0xf
	v_fmac_f32_dpp v165, v45, v117 row_shr:1 row_mask:0xf bank_mask:0xf
	v_fmac_f32_dpp v166, v46, v118 row_shr:1 row_mask:0xf bank_mask:0xf
	v_fmac_f32_dpp v167, v47, v119 row_shr:1 row_mask:0xf bank_mask:0xf
	v_fmac_f32_dpp v160, v48, v84 row_shr:2 row_mask:0xf bank_mask:0xf
	v_fmac_f32_dpp v161, v49, v85 row_shr:2 row_mask:0xf bank_mask:0xf
	v_fmac_f32_dpp v162, v50, v86 row_shr:2 row_mask:0xf bank_mask:0xf
	v_fmac_f32_dpp v163, v51, v87 row_shr:2 row_mask:0xf bank_mask:0xf
	v_fmac_f32_dpp v164, v44, v104 row_shr:2 row_mask:0xf bank_mask:0xf
	v_fmac_f32_dpp v165, v45, v105 row_shr:2 row_mask:0xf bank_mask:0xf
	v_fmac_f32_dpp v166, v46, v106 row_shr:2 row_mask:0xf bank_mask:0xf
	v_fmac_f32_dpp v167, v47, v107 row_shr:2 row_mask:0xf bank_mask:0xf
	v_pk_mul_f32 v[168:169], v[160:161], s[98:99]
	v_pk_mul_f32 v[170:171], v[162:163], s[98:99]
	v_exp_f32_e32 v168, v168
	v_exp_f32_e32 v169, v169
	v_exp_f32_e32 v170, v170
	v_exp_f32_e32 v171, v171
	v_pk_add_f32 v[168:169], v[168:169], s[100:101]
	v_pk_add_f32 v[170:171], v[170:171], s[100:101]
	v_rcp_f32_e32 v168, v168
	v_rcp_f32_e32 v169, v169
	v_rcp_f32_e32 v170, v170
	v_rcp_f32_e32 v171, v171
	v_mov_b64_e32 v[174:175], v[224:225]
	v_mul_f32_e32 v160, v160, v168
	v_mul_f32_e32 v161, v161, v169
	v_mul_f32_e32 v162, v162, v170
	v_mul_f32_e32 v163, v163, v171
	v_mul_f32_e32 v160, v164, v160
	v_mul_f32_e32 v161, v165, v161
	v_mul_f32_e32 v162, v166, v162
	v_mul_f32_e32 v163, v167, v163
	v_cvt_pk_bf16_f32 v172, v160, v161
	v_cvt_pk_bf16_f32 v173, v162, v163
	s_and_saveexec_b64 s[76:77], s[38:39]
	global_store_dwordx2 v[174:175], v[172:173], off
	s_or_b64 exec, exec, s[76:77]
	s_ashr_i32 s80, s71, 6
	s_lshl_b32 s80, s80, 2
	s_add_i32 s80, s80, 8
	v_add_u32_e32 v226, s80, v188
	v_mov_b64_e32 v[174:175], s[8:9]
	s_movk_i32 s80, 0x5800
	v_mad_i64_i32 v[174:175], s[78:79], v226, s80, v[174:175]
	v_lshl_add_u64 v[174:175], v[228:229], 2, v[174:175]
	s_and_saveexec_b64 s[76:77], s[40:41]
	global_store_dwordx4 v[174:175], v[48:51], off
	global_store_dwordx4 v[174:175], v[44:47], off offset:16
	s_or_b64 exec, exec, s[76:77]
	v_fma_f32 v208, v100, v24, v124
	v_fma_f32 v209, v101, v25, v125
	v_fma_f32 v210, v102, v26, v126
	v_fma_f32 v211, v103, v27, v127
	v_fma_f32 v212, v120, v20, v72
	v_fma_f32 v213, v121, v21, v73
	v_fma_f32 v214, v122, v22, v74
	v_fma_f32 v215, v123, v23, v75
	v_fmac_f32_dpp v208, v24, v88 row_shr:1 row_mask:0xf bank_mask:0xf
	v_fmac_f32_dpp v209, v25, v89 row_shr:1 row_mask:0xf bank_mask:0xf
	v_fmac_f32_dpp v210, v26, v90 row_shr:1 row_mask:0xf bank_mask:0xf
	v_fmac_f32_dpp v211, v27, v91 row_shr:1 row_mask:0xf bank_mask:0xf
	v_fmac_f32_dpp v212, v20, v116 row_shr:1 row_mask:0xf bank_mask:0xf
	v_fmac_f32_dpp v213, v21, v117 row_shr:1 row_mask:0xf bank_mask:0xf
	v_fmac_f32_dpp v214, v22, v118 row_shr:1 row_mask:0xf bank_mask:0xf
; DI float silu_fast(float x) { return x * __builtin_amdgcn_rcpf(1.f + __expf(-x)); }
; template <int CTRL> DI float dppf(float v) { return __builtin_bit_cast(float, __builtin_amdgcn_update_dpp(0, __builtin_bit_cast(int, v), CTRL, 0xf, 0xf, true)); }
; DI void Epi::fused(const f32x4 (&acc)[2][2][4][2], int pm, int pn, int wr, int wc, int fr, int fq) const {
;     ...
;             for (int m = 0; m < 4; ++m) {
;                 const f32x4 ca = acc[ai][bj][m][0], cb = acc[ai][bj][m][1];
;                 const int row = pm * 256 + ai * 128 + wr * 64 + m * 16 + fr;
;                 float o[4];
; #pragma unroll
;                 for (int e = 0; e < 4; ++e) {
;                     const float a1 = dppf<0x111>(ca[e]) + dppf<0x10F>(pa[e]), a2 = dppf<0x112>(ca[e]) + dppf<0x10E>(pa[e]);
;                     const float b1 = dppf<0x111>(cb[e]) + dppf<0x10F>(pb[e]), b2 = dppf<0x112>(cb[e]) + dppf<0x10E>(pb[e]);
;                     const float ya = fmaf(wa0[e], a2, fmaf(wa1[e], a1, fmaf(wa2[e], ca[e], ba[e])));
;                     const float yb = fmaf(wb0[e], b2, fmaf(wb1[e], b1, fmaf(wb2[e], cb[e], bb[e])));
;                     o[e] = silu_fast(ya) * yb; }
;                 if (m > 0 || fr >= 2) { u32x2 w; w.x = pk2(o[0], o[1]); w.y = pk2(o[2], o[3]); *(u32x2*)(E.d0 + (size_t)row * FFH + j0) = w; }
	v_fmac_f32_dpp v215, v23, v119 row_shr:1 row_mask:0xf bank_mask:0xf
	v_fmac_f32_dpp v208, v48, v88 row_shl:15 row_mask:0xf bank_mask:0xf
	v_fmac_f32_dpp v209, v49, v89 row_shl:15 row_mask:0xf bank_mask:0xf
	v_fmac_f32_dpp v210, v50, v90 row_shl:15 row_mask:0xf bank_mask:0xf
	v_fmac_f32_dpp v211, v51, v91 row_shl:15 row_mask:0xf bank_mask:0xf
	v_fmac_f32_dpp v212, v44, v116 row_shl:15 row_mask:0xf bank_mask:0xf
	v_fmac_f32_dpp v213, v45, v117 row_shl:15 row_mask:0xf bank_mask:0xf
	v_fmac_f32_dpp v214, v46, v118 row_shl:15 row_mask:0xf bank_mask:0xf
	v_fmac_f32_dpp v215, v47, v119 row_shl:15 row_mask:0xf bank_mask:0xf
	v_fmac_f32_dpp v208, v24, v84 row_shr:2 row_mask:0xf bank_mask:0xf
	v_fmac_f32_dpp v209, v25, v85 row_shr:2 row_mask:0xf bank_mask:0xf
	v_fmac_f32_dpp v210, v26, v86 row_shr:2 row_mask:0xf bank_mask:0xf
	v_fmac_f32_dpp v211, v27, v87 row_shr:2 row_mask:0xf bank_mask:0xf
	v_fmac_f32_dpp v212, v20, v104 row_shr:2 row_mask:0xf bank_mask:0xf
	v_fmac_f32_dpp v213, v21, v105 row_shr:2 row_mask:0xf bank_mask:0xf
	v_fmac_f32_dpp v214, v22, v106 row_shr:2 row_mask:0xf bank_mask:0xf
	v_fmac_f32_dpp v215, v23, v107 row_shr:2 row_mask:0xf bank_mask:0xf
	v_fmac_f32_dpp v208, v48, v84 row_shl:14 row_mask:0xf bank_mask:0xf
	v_fmac_f32_dpp v209, v49, v85 row_shl:14 row_mask:0xf bank_mask:0xf
	v_fmac_f32_dpp v210, v50, v86 row_shl:14 row_mask:0xf bank_mask:0xf
	v_fmac_f32_dpp v211, v51, v87 row_shl:14 row_mask:0xf bank_mask:0xf
	v_fmac_f32_dpp v212, v44, v104 row_shl:14 row_mask:0xf bank_mask:0xf
	v_fmac_f32_dpp v213, v45, v105 row_shl:14 row_mask:0xf bank_mask:0xf
	v_fmac_f32_dpp v214, v46, v106 row_shl:14 row_mask:0xf bank_mask:0xf
	v_fmac_f32_dpp v215, v47, v107 row_shl:14 row_mask:0xf bank_mask:0xf
	v_pk_mul_f32 v[216:217], v[208:209], s[98:99]
	v_pk_mul_f32 v[218:219], v[210:211], s[98:99]
	v_exp_f32_e32 v216, v216
	v_exp_f32_e32 v217, v217
	v_exp_f32_e32 v218, v218
	v_exp_f32_e32 v219, v219
	v_pk_add_f32 v[216:217], v[216:217], s[100:101]
	v_pk_add_f32 v[218:219], v[218:219], s[100:101]
	v_rcp_f32_e32 v216, v216
	v_rcp_f32_e32 v217, v217
	v_rcp_f32_e32 v218, v218
	v_rcp_f32_e32 v219, v219
	s_mov_b32 s80, 0x16000
	s_mov_b32 s81, 0
	v_lshl_add_u64 v[222:223], v[224:225], 0, s[80:81]
	v_mul_f32_e32 v208, v208, v216
	v_mul_f32_e32 v209, v209, v217
	v_mul_f32_e32 v210, v210, v218
	v_mul_f32_e32 v211, v211, v219
	v_mul_f32_e32 v208, v212, v208
	v_mul_f32_e32 v209, v213, v209
	v_mul_f32_e32 v210, v214, v210
	v_mul_f32_e32 v211, v215, v211
	v_cvt_pk_bf16_f32 v220, v208, v209
	v_cvt_pk_bf16_f32 v221, v210, v211
	global_store_dwordx2 v[222:223], v[220:221], off
	v_fma_f32 v160, v100, v28, v124
	v_fma_f32 v161, v101, v29, v125
	v_fma_f32 v162, v102, v30, v126
	v_fma_f32 v163, v103, v31, v127
	v_fma_f32 v164, v120, v32, v72
	v_fma_f32 v165, v121, v33, v73
	v_fma_f32 v166, v122, v34, v74
	v_fma_f32 v167, v123, v35, v75
	v_fmac_f32_dpp v160, v28, v88 row_shr:1 row_mask:0xf bank_mask:0xf
	v_fmac_f32_dpp v161, v29, v89 row_shr:1 row_mask:0xf bank_mask:0xf
	v_fmac_f32_dpp v162, v30, v90 row_shr:1 row_mask:0xf bank_mask:0xf
	v_fmac_f32_dpp v163, v31, v91 row_shr:1 row_mask:0xf bank_mask:0xf
	v_fmac_f32_dpp v164, v32, v116 row_shr:1 row_mask:0xf bank_mask:0xf
	v_fmac_f32_dpp v165, v33, v117 row_shr:1 row_mask:0xf bank_mask:0xf
	v_fmac_f32_dpp v166, v34, v118 row_shr:1 row_mask:0xf bank_mask:0xf
	v_fmac_f32_dpp v167, v35, v119 row_shr:1 row_mask:0xf bank_mask:0xf
	v_fmac_f32_dpp v160, v24, v88 row_shl:15 row_mask:0xf bank_mask:0xf
	v_fmac_f32_dpp v161, v25, v89 row_shl:15 row_mask:0xf bank_mask:0xf
	v_fmac_f32_dpp v162, v26, v90 row_shl:15 row_mask:0xf bank_mask:0xf
	v_fmac_f32_dpp v163, v27, v91 row_shl:15 row_mask:0xf bank_mask:0xf
	v_fmac_f32_dpp v164, v20, v116 row_shl:15 row_mask:0xf bank_mask:0xf
	v_fmac_f32_dpp v165, v21, v117 row_shl:15 row_mask:0xf bank_mask:0xf
	v_fmac_f32_dpp v166, v22, v118 row_shl:15 row_mask:0xf bank_mask:0xf
	v_fmac_f32_dpp v167, v23, v119 row_shl:15 row_mask:0xf bank_mask:0xf
	v_fmac_f32_dpp v160, v28, v84 row_shr:2 row_mask:0xf bank_mask:0xf
	v_fmac_f32_dpp v161, v29, v85 row_shr:2 row_mask:0xf bank_mask:0xf
	v_fmac_f32_dpp v162, v30, v86 row_shr:2 row_mask:0xf bank_mask:0xf
	v_fmac_f32_dpp v163, v31, v87 row_shr:2 row_mask:0xf bank_mask:0xf
	v_fmac_f32_dpp v164, v32, v104 row_shr:2 row_mask:0xf bank_mask:0xf
	v_fmac_f32_dpp v165, v33, v105 row_shr:2 row_mask:0xf bank_mask:0xf
	v_fmac_f32_dpp v166, v34, v106 row_shr:2 row_mask:0xf bank_mask:0xf
	v_fmac_f32_dpp v167, v35, v107 row_shr:2 row_mask:0xf bank_mask:0xf
	v_fmac_f32_dpp v160, v24, v84 row_shl:14 row_mask:0xf bank_mask:0xf
	v_fmac_f32_dpp v161, v25, v85 row_shl:14 row_mask:0xf bank_mask:0xf
	v_fmac_f32_dpp v162, v26, v86 row_shl:14 row_mask:0xf bank_mask:0xf
	v_fmac_f32_dpp v163, v27, v87 row_shl:14 row_mask:0xf bank_mask:0xf
	v_fmac_f32_dpp v164, v20, v104 row_shl:14 row_mask:0xf bank_mask:0xf
; DI float silu_fast(float x) { return x * __builtin_amdgcn_rcpf(1.f + __expf(-x)); }
; template <int CTRL> DI float dppf(float v) { return __builtin_bit_cast(float, __builtin_amdgcn_update_dpp(0, __builtin_bit_cast(int, v), CTRL, 0xf, 0xf, true)); }
; DI void Epi::fused(const f32x4 (&acc)[2][2][4][2], int pm, int pn, int wr, int wc, int fr, int fq) const {
;     ...
;             for (int m = 0; m < 4; ++m) {
;                 const f32x4 ca = acc[ai][bj][m][0], cb = acc[ai][bj][m][1];
;                 const int row = pm * 256 + ai * 128 + wr * 64 + m * 16 + fr;
;                 float o[4];
; #pragma unroll
;                 for (int e = 0; e < 4; ++e) {
;                     const float a1 = dppf<0x111>(ca[e]) + dppf<0x10F>(pa[e]), a2 = dppf<0x112>(ca[e]) + dppf<0x10E>(pa[e]);
;                     const float b1 = dppf<0x111>(cb[e]) + dppf<0x10F>(pb[e]), b2 = dppf<0x112>(cb[e]) + dppf<0x10E>(pb[e]);
;                     const float ya = fmaf(wa0[e], a2, fmaf(wa1[e], a1, fmaf(wa2[e], ca[e], ba[e])));
;                     const float yb = fmaf(wb0[e], b2, fmaf(wb1[e], b1, fmaf(wb2[e], cb[e], bb[e])));
;                     o[e] = silu_fast(ya) * yb; }
;                 if (m > 0 || fr >= 2) { u32x2 w; w.x = pk2(o[0], o[1]); w.y = pk2(o[2], o[3]); *(u32x2*)(E.d0 + (size_t)row * FFH + j0) = w; }
;                 if ((m == 0 && fr < 2) || (m == 3 && fr >= 14)) { float* hb = E.f0 + ((size_t)(row >> 6) * 4 + (m == 0 ? fr : fr - 12)) * FF2 + ncol; *(f32x4*)hb = ca; *(f32x4*)(hb + 4) = cb; }
	v_fmac_f32_dpp v165, v21, v105 row_shl:14 row_mask:0xf bank_mask:0xf
	v_fmac_f32_dpp v166, v22, v106 row_shl:14 row_mask:0xf bank_mask:0xf
	v_fmac_f32_dpp v167, v23, v107 row_shl:14 row_mask:0xf bank_mask:0xf
	v_pk_mul_f32 v[168:169], v[160:161], s[98:99]
	v_pk_mul_f32 v[170:171], v[162:163], s[98:99]
	v_exp_f32_e32 v168, v168
	v_exp_f32_e32 v169, v169
	v_exp_f32_e32 v170, v170
	v_exp_f32_e32 v171, v171
	v_pk_add_f32 v[168:169], v[168:169], s[100:101]
	v_pk_add_f32 v[170:171], v[170:171], s[100:101]
	v_rcp_f32_e32 v168, v168
	v_rcp_f32_e32 v169, v169
	v_rcp_f32_e32 v170, v170
	v_rcp_f32_e32 v171, v171
	s_mov_b32 s80, 0x2c000
	s_mov_b32 s81, 0
	v_lshl_add_u64 v[174:175], v[224:225], 0, s[80:81]
	v_mul_f32_e32 v160, v160, v168
	v_mul_f32_e32 v161, v161, v169
	v_mul_f32_e32 v162, v162, v170
	v_mul_f32_e32 v163, v163, v171
	v_mul_f32_e32 v160, v164, v160
	v_mul_f32_e32 v161, v165, v161
	v_mul_f32_e32 v162, v166, v162
	v_mul_f32_e32 v163, v167, v163
	v_cvt_pk_bf16_f32 v172, v160, v161
	v_cvt_pk_bf16_f32 v173, v162, v163
	global_store_dwordx2 v[174:175], v[172:173], off
	v_fma_f32 v208, v100, v8, v124
	v_fma_f32 v209, v101, v9, v125
	v_fma_f32 v210, v102, v10, v126
	v_fma_f32 v211, v103, v11, v127
	v_fma_f32 v212, v120, v4, v72
	v_fma_f32 v213, v121, v5, v73
	v_fma_f32 v214, v122, v6, v74
	v_fma_f32 v215, v123, v7, v75
	v_fmac_f32_dpp v208, v8, v88 row_shr:1 row_mask:0xf bank_mask:0xf
	v_fmac_f32_dpp v209, v9, v89 row_shr:1 row_mask:0xf bank_mask:0xf
	v_fmac_f32_dpp v210, v10, v90 row_shr:1 row_mask:0xf bank_mask:0xf
	v_fmac_f32_dpp v211, v11, v91 row_shr:1 row_mask:0xf bank_mask:0xf
	v_fmac_f32_dpp v212, v4, v116 row_shr:1 row_mask:0xf bank_mask:0xf
	v_fmac_f32_dpp v213, v5, v117 row_shr:1 row_mask:0xf bank_mask:0xf
	v_fmac_f32_dpp v214, v6, v118 row_shr:1 row_mask:0xf bank_mask:0xf
	v_fmac_f32_dpp v215, v7, v119 row_shr:1 row_mask:0xf bank_mask:0xf
	v_fmac_f32_dpp v208, v28, v88 row_shl:15 row_mask:0xf bank_mask:0xf
	v_fmac_f32_dpp v209, v29, v89 row_shl:15 row_mask:0xf bank_mask:0xf
	v_fmac_f32_dpp v210, v30, v90 row_shl:15 row_mask:0xf bank_mask:0xf
	v_fmac_f32_dpp v211, v31, v91 row_shl:15 row_mask:0xf bank_mask:0xf
	v_fmac_f32_dpp v212, v32, v116 row_shl:15 row_mask:0xf bank_mask:0xf
	v_fmac_f32_dpp v213, v33, v117 row_shl:15 row_mask:0xf bank_mask:0xf
	v_fmac_f32_dpp v214, v34, v118 row_shl:15 row_mask:0xf bank_mask:0xf
	v_fmac_f32_dpp v215, v35, v119 row_shl:15 row_mask:0xf bank_mask:0xf
	v_fmac_f32_dpp v208, v8, v84 row_shr:2 row_mask:0xf bank_mask:0xf
	v_fmac_f32_dpp v209, v9, v85 row_shr:2 row_mask:0xf bank_mask:0xf
	v_fmac_f32_dpp v210, v10, v86 row_shr:2 row_mask:0xf bank_mask:0xf
	v_fmac_f32_dpp v211, v11, v87 row_shr:2 row_mask:0xf bank_mask:0xf
	v_fmac_f32_dpp v212, v4, v104 row_shr:2 row_mask:0xf bank_mask:0xf
	v_fmac_f32_dpp v213, v5, v105 row_shr:2 row_mask:0xf bank_mask:0xf
	v_fmac_f32_dpp v214, v6, v106 row_shr:2 row_mask:0xf bank_mask:0xf
	v_fmac_f32_dpp v215, v7, v107 row_shr:2 row_mask:0xf bank_mask:0xf
	v_fmac_f32_dpp v208, v28, v84 row_shl:14 row_mask:0xf bank_mask:0xf
	v_fmac_f32_dpp v209, v29, v85 row_shl:14 row_mask:0xf bank_mask:0xf
	v_fmac_f32_dpp v210, v30, v86 row_shl:14 row_mask:0xf bank_mask:0xf
	v_fmac_f32_dpp v211, v31, v87 row_shl:14 row_mask:0xf bank_mask:0xf
	v_fmac_f32_dpp v212, v32, v104 row_shl:14 row_mask:0xf bank_mask:0xf
	v_fmac_f32_dpp v213, v33, v105 row_shl:14 row_mask:0xf bank_mask:0xf
	v_fmac_f32_dpp v214, v34, v106 row_shl:14 row_mask:0xf bank_mask:0xf
	v_fmac_f32_dpp v215, v35, v107 row_shl:14 row_mask:0xf bank_mask:0xf
	v_pk_mul_f32 v[216:217], v[208:209], s[98:99]
	v_pk_mul_f32 v[218:219], v[210:211], s[98:99]
	v_exp_f32_e32 v216, v216
	v_exp_f32_e32 v217, v217
	v_exp_f32_e32 v218, v218
	v_exp_f32_e32 v219, v219
	v_pk_add_f32 v[216:217], v[216:217], s[100:101]
	v_pk_add_f32 v[218:219], v[218:219], s[100:101]
	v_rcp_f32_e32 v216, v216
	v_rcp_f32_e32 v217, v217
	v_rcp_f32_e32 v218, v218
	v_rcp_f32_e32 v219, v219
	s_mov_b32 s80, 0x42000
	s_mov_b32 s81, 0
	v_lshl_add_u64 v[222:223], v[224:225], 0, s[80:81]
	v_mul_f32_e32 v208, v208, v216
	v_mul_f32_e32 v209, v209, v217
	v_mul_f32_e32 v210, v210, v218
	v_mul_f32_e32 v211, v211, v219
	v_mul_f32_e32 v208, v212, v208
	v_mul_f32_e32 v209, v213, v209
	v_mul_f32_e32 v210, v214, v210
	v_mul_f32_e32 v211, v215, v211
	v_cvt_pk_bf16_f32 v220, v208, v209
	v_cvt_pk_bf16_f32 v221, v210, v211
	global_store_dwordx2 v[222:223], v[220:221], off
	s_ashr_i32 s80, s71, 6
	s_lshl_b32 s80, s80, 2
	s_add_i32 s80, s80, 8
	v_add_u32_e32 v226, s80, v190
	v_mov_b64_e32 v[222:223], s[8:9]
	s_movk_i32 s80, 0x5800
	v_mad_i64_i32 v[222:223], s[78:79], v226, s80, v[222:223]
	v_lshl_add_u64 v[222:223], v[228:229], 2, v[222:223]
	s_and_saveexec_b64 s[76:77], s[42:43]
	global_store_dwordx4 v[222:223], v[8:11], off
	global_store_dwordx4 v[222:223], v[4:7], off offset:16
	s_or_b64 exec, exec, s[76:77]
